# pointwise GEMM epilogue (P4): touch-prefetch of the 16 gate rows ahead of its serialized load-wait chain
# baseline (speedup 1.0000x reference)
; __device__ __forceinline__ unsigned cvt_pk_bf16(float lo, float hi) { unsigned r; asm volatile("v_cvt_pk_bf16_f32 %0, %1, %2" : "=v"(r) : "v"(lo), "v"(hi)); return r; }
; __device__ __forceinline__ float bflo(unsigned u) { return __uint_as_float(u << 16); }
; __device__ __forceinline__ float bfhi(unsigned u) { return __uint_as_float(u & 0xffff0000u); }
; __device__ __forceinline__ float silu_f(float v) { return v / (1.f + __expf(-v)); }
;     __device__ __forceinline__ void operator()(const pg8::f32x4 (&acc)[2][2][4][2], const pg8::Unit& u, int wr, int wc, int fr, int fq) const {
;         const int row0 = u.pm * 256 + wr * 64 + fr, col0 = u.pn * 256 + wc * 32 + 8 * fq;
; #pragma unroll
;         for (int ai = 0; ai < 2; ++ai)
; #pragma unroll
;             for (int m = 0; m < 4; ++m) { const size_t row = (size_t)(row0 + ai * 128 + m * 16);
; #pragma unroll
;                 for (int bj = 0; bj < 2; ++bj) { const pg8::f32x4 v0 = acc[ai][bj][m][0], v1 = acc[ai][bj][m][1];
;                     const u32x4 gz = *(const u32x4*)(Z + row * DIN + goff + col0 + bj * 128); u32x4 w;
;                     w.x = pg8::cvt_pk_bf16(v0[0] * silu_f(bflo(gz.x)), v0[1] * silu_f(bfhi(gz.x))); w.y = pg8::cvt_pk_bf16(v0[2] * silu_f(bflo(gz.y)), v0[3] * silu_f(bfhi(gz.y)));
;                     w.z = pg8::cvt_pk_bf16(v1[0] * silu_f(bflo(gz.z)), v1[1] * silu_f(bfhi(gz.z))); w.w = pg8::cvt_pk_bf16(v1[2] * silu_f(bflo(gz.w)), v1[3] * silu_f(bfhi(gz.w)));
;                     *(u32x4*)(O + row * DM + coff + col0 + bj * 128) = w; } }
.LBB0_555:
	v_readlane_b32 s12, v254, 0
	v_lshl_or_b32 v130, s50, 8, v170
	v_readlane_b32 s13, v254, 1
	v_lshl_add_u32 v160, s52, 8, v168
	v_ashrrev_i32_e32 v131, 31, v130
	v_mov_b64_e32 v[162:163], s[12:13]
	v_mad_i64_i32 v[132:133], s[12:13], v160, s75, v[162:163]
	v_lshlrev_b64 v[144:145], 1, v[130:131]
	v_lshl_add_u64 v[130:131], v[132:133], 0, v[144:145]
	s_mov_b64 s[26:27], 0x3000
	v_lshl_add_u64 v[166:167], v[130:131], 0, s[26:27]
	v_add_co_u32_e32 v130, vcc, 0x3000, v130
	v_ashrrev_i32_e32 v161, 31, v160
	s_nop 0
	v_addc_co_u32_e32 v131, vcc, 0, v131, vcc
	s_mov_b32 s59, 0
	global_load_dword v197, v[130:131], off offset:256
	s_mov_b32 s58, 0x34000
	v_lshl_add_u64 v[250:251], v[130:131], 0, s[58:59]
	global_load_dword v197, v[250:251], off
	global_load_dword v197, v[250:251], off offset:256
	s_mov_b32 s58, 0x68000
	v_lshl_add_u64 v[252:253], v[130:131], 0, s[58:59]
	global_load_dword v197, v[252:253], off
	global_load_dword v197, v[252:253], off offset:256
	s_mov_b32 s58, 0x9c000
	v_lshl_add_u64 v[250:251], v[130:131], 0, s[58:59]
	global_load_dword v197, v[250:251], off
	global_load_dword v197, v[250:251], off offset:256
	s_mov_b32 s58, 0x1a0000
	v_lshl_add_u64 v[252:253], v[130:131], 0, s[58:59]
	global_load_dword v197, v[252:253], off
	global_load_dword v197, v[252:253], off offset:256
	s_mov_b32 s58, 0x1d4000
	v_lshl_add_u64 v[250:251], v[130:131], 0, s[58:59]
	global_load_dword v197, v[250:251], off
	global_load_dword v197, v[250:251], off offset:256
	s_mov_b32 s58, 0x208000
	v_lshl_add_u64 v[252:253], v[130:131], 0, s[58:59]
	global_load_dword v197, v[252:253], off
	global_load_dword v197, v[252:253], off offset:256
	s_mov_b32 s58, 0x23c000
	v_lshl_add_u64 v[250:251], v[130:131], 0, s[58:59]
	global_load_dword v197, v[250:251], off
	global_load_dword v197, v[250:251], off offset:256
	global_load_dwordx4 v[130:133], v[130:131], off
	v_lshlrev_b64 v[164:165], 12, v[160:161]
	s_mov_b64 s[50:51], -1
	s_waitcnt vmcnt(0)
	v_lshlrev_b32_e32 v161, 16, v130
	v_mul_f32_e32 v172, 0xbfb8aa3b, v161
	v_exp_f32_e32 v172, v172
	v_and_b32_e32 v130, 0xffff0000, v130
	v_add_f32_e32 v172, 1.0, v172
	v_div_scale_f32 v173, s[12:13], v172, v172, v161
	v_rcp_f32_e32 v174, v173
	s_nop 0
	v_fma_f32 v175, -v173, v174, 1.0
	v_fmac_f32_e32 v174, v175, v174
	v_div_scale_f32 v175, vcc, v161, v172, v161
	v_mul_f32_e32 v176, v175, v174
	v_fma_f32 v177, -v173, v176, v175
	v_fmac_f32_e32 v176, v177, v174
	v_fma_f32 v173, -v173, v176, v175
	v_div_fmas_f32 v173, v173, v174, v176
	v_div_fixup_f32 v161, v173, v172, v161
	v_mul_f32_e32 v126, v126, v161
	v_mul_f32_e32 v161, 0xbfb8aa3b, v130
	v_exp_f32_e32 v161, v161
	s_nop 0
	v_add_f32_e32 v161, 1.0, v161
	v_div_scale_f32 v172, s[12:13], v161, v161, v130
	v_rcp_f32_e32 v173, v172
	s_nop 0
	v_fma_f32 v174, -v172, v173, 1.0
	v_fmac_f32_e32 v173, v174, v173
	v_div_scale_f32 v174, vcc, v130, v161, v130
	v_mul_f32_e32 v175, v174, v173
	v_fma_f32 v176, -v172, v175, v174
	v_fmac_f32_e32 v175, v176, v173
	v_fma_f32 v172, -v172, v175, v174
	v_div_fmas_f32 v172, v172, v173, v175
	v_div_fixup_f32 v130, v172, v161, v130
	v_mul_f32_e32 v127, v127, v130
	v_cvt_pk_bf16_f32 v126, v126, v127
	v_lshlrev_b32_e32 v127, 16, v131
	v_mul_f32_e32 v130, 0xbfb8aa3b, v127
	v_exp_f32_e32 v130, v130
	s_nop 0
	v_add_f32_e32 v130, 1.0, v130
	v_div_scale_f32 v161, s[12:13], v130, v130, v127
	v_rcp_f32_e32 v172, v161
	s_nop 0
	v_fma_f32 v173, -v161, v172, 1.0
	v_fmac_f32_e32 v172, v173, v172
	v_div_scale_f32 v173, vcc, v127, v130, v127
	v_mul_f32_e32 v174, v173, v172
	v_fma_f32 v175, -v161, v174, v173
	v_fmac_f32_e32 v174, v175, v172
	v_fma_f32 v161, -v161, v174, v173
	v_div_fmas_f32 v161, v161, v172, v174
	v_div_fixup_f32 v127, v161, v130, v127
	v_mul_f32_e32 v127, v128, v127
	v_and_b32_e32 v128, 0xffff0000, v131
	v_mul_f32_e32 v130, 0xbfb8aa3b, v128
	v_exp_f32_e32 v130, v130
	s_nop 0
	v_add_f32_e32 v130, 1.0, v130
	v_div_scale_f32 v131, s[12:13], v130, v130, v128
	v_rcp_f32_e32 v161, v131
	s_nop 0
	v_fma_f32 v172, -v131, v161, 1.0
	v_fmac_f32_e32 v161, v172, v161
	v_div_scale_f32 v172, vcc, v128, v130, v128
	v_mul_f32_e32 v173, v172, v161
	v_fma_f32 v174, -v131, v173, v172
	v_fmac_f32_e32 v173, v174, v161
	v_fma_f32 v131, -v131, v173, v172
	v_div_fmas_f32 v131, v131, v161, v173
	v_div_fixup_f32 v128, v131, v130, v128
	v_mul_f32_e32 v128, v129, v128
	v_cvt_pk_bf16_f32 v127, v127, v128
	v_lshlrev_b32_e32 v128, 16, v132
	v_mul_f32_e32 v129, 0xbfb8aa3b, v128
	v_exp_f32_e32 v129, v129
	s_nop 0
	v_add_f32_e32 v129, 1.0, v129
	v_div_scale_f32 v130, s[12:13], v129, v129, v128
	v_rcp_f32_e32 v131, v130
	s_nop 0
	v_fma_f32 v161, -v130, v131, 1.0
	v_fmac_f32_e32 v131, v161, v131
	v_div_scale_f32 v161, vcc, v128, v129, v128
	v_mul_f32_e32 v172, v161, v131
	v_fma_f32 v173, -v130, v172, v161
	v_fmac_f32_e32 v172, v173, v131
	v_fma_f32 v130, -v130, v172, v161
	v_div_fmas_f32 v130, v130, v131, v172
	v_div_fixup_f32 v128, v130, v129, v128
	v_mul_f32_e32 v122, v122, v128
	v_and_b32_e32 v128, 0xffff0000, v132
	v_mul_f32_e32 v129, 0xbfb8aa3b, v128
	v_exp_f32_e32 v129, v129
	s_nop 0
	v_add_f32_e32 v129, 1.0, v129
	v_div_scale_f32 v130, s[12:13], v129, v129, v128
	v_rcp_f32_e32 v131, v130
	s_nop 0
	v_fma_f32 v132, -v130, v131, 1.0
	v_fmac_f32_e32 v131, v132, v131
	v_div_scale_f32 v132, vcc, v128, v129, v128
	v_mul_f32_e32 v161, v132, v131
	v_fma_f32 v172, -v130, v161, v132
	v_fmac_f32_e32 v161, v172, v131
	v_fma_f32 v130, -v130, v161, v132
	v_div_fmas_f32 v130, v130, v131, v161
	v_div_fixup_f32 v128, v130, v129, v128
	v_mul_f32_e32 v123, v123, v128
	v_cvt_pk_bf16_f32 v128, v122, v123
	v_lshlrev_b32_e32 v122, 16, v133
	v_mul_f32_e32 v123, 0xbfb8aa3b, v122
	v_exp_f32_e32 v123, v123
	s_nop 0
	v_add_f32_e32 v123, 1.0, v123
	v_div_scale_f32 v129, s[12:13], v123, v123, v122
	v_rcp_f32_e32 v130, v129
	s_nop 0
	v_fma_f32 v131, -v129, v130, 1.0
	v_fmac_f32_e32 v130, v131, v130
	v_div_scale_f32 v131, vcc, v122, v123, v122
	v_mul_f32_e32 v132, v131, v130
	v_fma_f32 v161, -v129, v132, v131
	v_fmac_f32_e32 v132, v161, v130
	v_fma_f32 v129, -v129, v132, v131
	v_div_fmas_f32 v129, v129, v130, v132
	v_div_fixup_f32 v122, v129, v123, v122
	v_and_b32_e32 v123, 0xffff0000, v133
	v_mul_f32_e32 v122, v124, v122
	v_mul_f32_e32 v124, 0xbfb8aa3b, v123
	v_exp_f32_e32 v124, v124
	s_nop 0
	v_add_f32_e32 v124, 1.0, v124
	v_div_scale_f32 v129, s[12:13], v124, v124, v123
	v_rcp_f32_e32 v130, v129
	s_nop 0
	v_fma_f32 v131, -v129, v130, 1.0
	v_fmac_f32_e32 v130, v131, v130
	v_div_scale_f32 v131, vcc, v123, v124, v123
	v_mul_f32_e32 v132, v131, v130
	v_fma_f32 v133, -v129, v132, v131
	v_fmac_f32_e32 v132, v133, v130
	v_fma_f32 v129, -v129, v132, v131
	v_div_fmas_f32 v129, v129, v130, v132
	v_div_fixup_f32 v123, v129, v124, v123
	v_mul_f32_e32 v123, v125, v123
	v_cvt_pk_bf16_f32 v129, v122, v123
	v_lshl_add_u64 v[122:123], s[72:73], 0, v[164:165]
	v_lshl_add_u64 v[130:131], v[122:123], 0, v[144:145]
	global_store_dwordx4 v[130:131], v[126:129], off
	global_load_dwordx4 v[122:125], v[166:167], off offset:256
	s_waitcnt vmcnt(0)
; __device__ __forceinline__ unsigned cvt_pk_bf16(float lo, float hi) { unsigned r; asm volatile("v_cvt_pk_bf16_f32 %0, %1, %2" : "=v"(r) : "v"(lo), "v"(hi)); return r; }
; __device__ __forceinline__ float bflo(unsigned u) { return __uint_as_float(u << 16); }
; __device__ __forceinline__ float bfhi(unsigned u) { return __uint_as_float(u & 0xffff0000u); }
; __device__ __forceinline__ float silu_f(float v) { return v / (1.f + __expf(-v)); }
;     __device__ __forceinline__ void operator()(const pg8::f32x4 (&acc)[2][2][4][2], const pg8::Unit& u, int wr, int wc, int fr, int fq) const {
;     ...
;             for (int m = 0; m < 4; ++m) { const size_t row = (size_t)(row0 + ai * 128 + m * 16);
; #pragma unroll
;                 for (int bj = 0; bj < 2; ++bj) { const pg8::f32x4 v0 = acc[ai][bj][m][0], v1 = acc[ai][bj][m][1];
;                     const u32x4 gz = *(const u32x4*)(Z + row * DIN + goff + col0 + bj * 128); u32x4 w;
;                     w.x = pg8::cvt_pk_bf16(v0[0] * silu_f(bflo(gz.x)), v0[1] * silu_f(bfhi(gz.x))); w.y = pg8::cvt_pk_bf16(v0[2] * silu_f(bflo(gz.y)), v0[3] * silu_f(bfhi(gz.y)));
;                     w.z = pg8::cvt_pk_bf16(v1[0] * silu_f(bflo(gz.z)), v1[1] * silu_f(bfhi(gz.z))); w.w = pg8::cvt_pk_bf16(v1[2] * silu_f(bflo(gz.w)), v1[3] * silu_f(bfhi(gz.w)));
;                     *(u32x4*)(O + row * DM + coff + col0 + bj * 128) = w; } }
	v_lshlrev_b32_e32 v126, 16, v122
	v_mul_f32_e32 v127, 0xbfb8aa3b, v126
	v_exp_f32_e32 v127, v127
	v_and_b32_e32 v122, 0xffff0000, v122
	v_add_f32_e32 v127, 1.0, v127
	v_div_scale_f32 v128, s[12:13], v127, v127, v126
	v_rcp_f32_e32 v129, v128
	s_nop 0
	v_fma_f32 v132, -v128, v129, 1.0
	v_fmac_f32_e32 v129, v132, v129
	v_div_scale_f32 v132, vcc, v126, v127, v126
	v_mul_f32_e32 v133, v132, v129
	v_fma_f32 v161, -v128, v133, v132
	v_fmac_f32_e32 v133, v161, v129
	v_fma_f32 v128, -v128, v133, v132
	v_div_fmas_f32 v128, v128, v129, v133
	v_div_fixup_f32 v126, v128, v127, v126
	v_mul_f32_e32 v118, v118, v126
	v_mul_f32_e32 v126, 0xbfb8aa3b, v122
	v_exp_f32_e32 v126, v126
	s_nop 0
	v_add_f32_e32 v126, 1.0, v126
	v_div_scale_f32 v127, s[12:13], v126, v126, v122
	v_rcp_f32_e32 v128, v127
	s_nop 0
	v_fma_f32 v129, -v127, v128, 1.0
	v_fmac_f32_e32 v128, v129, v128
	v_div_scale_f32 v129, vcc, v122, v126, v122
	v_mul_f32_e32 v132, v129, v128
	v_fma_f32 v133, -v127, v132, v129
	v_fmac_f32_e32 v132, v133, v128
	v_fma_f32 v127, -v127, v132, v129
	v_div_fmas_f32 v127, v127, v128, v132
	v_div_fixup_f32 v122, v127, v126, v122
	v_mul_f32_e32 v119, v119, v122
	v_cvt_pk_bf16_f32 v118, v118, v119
	v_lshlrev_b32_e32 v119, 16, v123
	v_mul_f32_e32 v122, 0xbfb8aa3b, v119
	v_exp_f32_e32 v122, v122
	s_nop 0
	v_add_f32_e32 v122, 1.0, v122
	v_div_scale_f32 v126, s[12:13], v122, v122, v119
	v_rcp_f32_e32 v127, v126
	s_nop 0
	v_fma_f32 v128, -v126, v127, 1.0
	v_fmac_f32_e32 v127, v128, v127
	v_div_scale_f32 v128, vcc, v119, v122, v119
	v_mul_f32_e32 v129, v128, v127
	v_fma_f32 v132, -v126, v129, v128
	v_fmac_f32_e32 v129, v132, v127
	v_fma_f32 v126, -v126, v129, v128
	v_div_fmas_f32 v126, v126, v127, v129
	v_div_fixup_f32 v119, v126, v122, v119
	v_mul_f32_e32 v119, v120, v119
	v_and_b32_e32 v120, 0xffff0000, v123
	v_mul_f32_e32 v122, 0xbfb8aa3b, v120
	v_exp_f32_e32 v122, v122
	s_nop 0
	v_add_f32_e32 v122, 1.0, v122
	v_div_scale_f32 v123, s[12:13], v122, v122, v120
	v_rcp_f32_e32 v126, v123
	s_nop 0
	v_fma_f32 v127, -v123, v126, 1.0
	v_fmac_f32_e32 v126, v127, v126
	v_div_scale_f32 v127, vcc, v120, v122, v120
	v_mul_f32_e32 v128, v127, v126
	v_fma_f32 v129, -v123, v128, v127
	v_fmac_f32_e32 v128, v129, v126
	v_fma_f32 v123, -v123, v128, v127
	v_div_fmas_f32 v123, v123, v126, v128
	v_div_fixup_f32 v120, v123, v122, v120
	v_mul_f32_e32 v120, v121, v120
	v_cvt_pk_bf16_f32 v119, v119, v120
	v_lshlrev_b32_e32 v120, 16, v124
	v_mul_f32_e32 v121, 0xbfb8aa3b, v120
	v_exp_f32_e32 v121, v121
	s_nop 0
	v_add_f32_e32 v121, 1.0, v121
	v_div_scale_f32 v122, s[12:13], v121, v121, v120
	v_rcp_f32_e32 v123, v122
	s_nop 0
	v_fma_f32 v126, -v122, v123, 1.0
	v_fmac_f32_e32 v123, v126, v123
	v_div_scale_f32 v126, vcc, v120, v121, v120
	v_mul_f32_e32 v127, v126, v123
	v_fma_f32 v128, -v122, v127, v126
	v_fmac_f32_e32 v127, v128, v123
	v_fma_f32 v122, -v122, v127, v126
	v_div_fmas_f32 v122, v122, v123, v127
	v_div_fixup_f32 v120, v122, v121, v120
	v_mul_f32_e32 v114, v114, v120
	v_and_b32_e32 v120, 0xffff0000, v124
	v_mul_f32_e32 v121, 0xbfb8aa3b, v120
	v_exp_f32_e32 v121, v121
	s_nop 0
	v_add_f32_e32 v121, 1.0, v121
	v_div_scale_f32 v122, s[12:13], v121, v121, v120
	v_rcp_f32_e32 v123, v122
	s_nop 0
	v_fma_f32 v124, -v122, v123, 1.0
	v_fmac_f32_e32 v123, v124, v123
	v_div_scale_f32 v124, vcc, v120, v121, v120
	v_mul_f32_e32 v126, v124, v123
	v_fma_f32 v127, -v122, v126, v124
	v_fmac_f32_e32 v126, v127, v123
	v_fma_f32 v122, -v122, v126, v124
	v_div_fmas_f32 v122, v122, v123, v126
	v_div_fixup_f32 v120, v122, v121, v120
	v_mul_f32_e32 v115, v115, v120
	v_cvt_pk_bf16_f32 v120, v114, v115
	v_lshlrev_b32_e32 v114, 16, v125
	v_mul_f32_e32 v115, 0xbfb8aa3b, v114
	v_exp_f32_e32 v115, v115
	s_nop 0
	v_add_f32_e32 v115, 1.0, v115
	v_div_scale_f32 v121, s[12:13], v115, v115, v114
	v_rcp_f32_e32 v122, v121
	s_nop 0
	v_fma_f32 v123, -v121, v122, 1.0
	v_fmac_f32_e32 v122, v123, v122
	v_div_scale_f32 v123, vcc, v114, v115, v114
	v_mul_f32_e32 v124, v123, v122
	v_fma_f32 v126, -v121, v124, v123
	v_fmac_f32_e32 v124, v126, v122
	v_fma_f32 v121, -v121, v124, v123
	v_div_fmas_f32 v121, v121, v122, v124
	v_div_fixup_f32 v114, v121, v115, v114
	v_and_b32_e32 v115, 0xffff0000, v125
	v_mul_f32_e32 v114, v116, v114
	v_mul_f32_e32 v116, 0xbfb8aa3b, v115
	v_exp_f32_e32 v116, v116
	s_nop 0
	v_add_f32_e32 v116, 1.0, v116
	v_div_scale_f32 v121, s[12:13], v116, v116, v115
	v_rcp_f32_e32 v122, v121
	s_nop 0
	v_fma_f32 v123, -v121, v122, 1.0
	v_fmac_f32_e32 v122, v123, v122
	v_div_scale_f32 v123, vcc, v115, v116, v115
	v_mul_f32_e32 v124, v123, v122
	v_fma_f32 v125, -v121, v124, v123
	v_fmac_f32_e32 v124, v125, v122
	v_fma_f32 v121, -v121, v124, v123
	v_div_fmas_f32 v121, v121, v122, v124
	v_div_fixup_f32 v115, v121, v116, v115
	v_mul_f32_e32 v115, v117, v115
	v_cvt_pk_bf16_f32 v121, v114, v115
	v_or_b32_e32 v114, 16, v160
	v_ashrrev_i32_e32 v115, 31, v114
	global_store_dwordx4 v[130:131], v[118:121], off offset:256
	s_nop 1
	v_lshlrev_b64 v[118:119], 12, v[114:115]
	v_mad_i64_i32 v[114:115], s[12:13], v114, s75, v[162:163]
	v_lshl_add_u64 v[114:115], v[114:115], 0, v[144:145]
	v_lshl_add_u64 v[120:121], v[114:115], 0, s[26:27]
	v_add_co_u32_e32 v114, vcc, s5, v114
	s_nop 1
	v_addc_co_u32_e32 v115, vcc, 0, v115, vcc
	global_load_dwordx4 v[114:117], v[114:115], off
	s_waitcnt vmcnt(0)
; __device__ __forceinline__ unsigned cvt_pk_bf16(float lo, float hi) { unsigned r; asm volatile("v_cvt_pk_bf16_f32 %0, %1, %2" : "=v"(r) : "v"(lo), "v"(hi)); return r; }
; __device__ __forceinline__ float bflo(unsigned u) { return __uint_as_float(u << 16); }
; __device__ __forceinline__ float bfhi(unsigned u) { return __uint_as_float(u & 0xffff0000u); }
; __device__ __forceinline__ float silu_f(float v) { return v / (1.f + __expf(-v)); }
;     __device__ __forceinline__ void operator()(const pg8::f32x4 (&acc)[2][2][4][2], const pg8::Unit& u, int wr, int wc, int fr, int fq) const {
;     ...
;             for (int m = 0; m < 4; ++m) { const size_t row = (size_t)(row0 + ai * 128 + m * 16);
; #pragma unroll
;                 for (int bj = 0; bj < 2; ++bj) { const pg8::f32x4 v0 = acc[ai][bj][m][0], v1 = acc[ai][bj][m][1];
;                     const u32x4 gz = *(const u32x4*)(Z + row * DIN + goff + col0 + bj * 128); u32x4 w;
;                     w.x = pg8::cvt_pk_bf16(v0[0] * silu_f(bflo(gz.x)), v0[1] * silu_f(bfhi(gz.x))); w.y = pg8::cvt_pk_bf16(v0[2] * silu_f(bflo(gz.y)), v0[3] * silu_f(bfhi(gz.y)));
;                     w.z = pg8::cvt_pk_bf16(v1[0] * silu_f(bflo(gz.z)), v1[1] * silu_f(bfhi(gz.z))); w.w = pg8::cvt_pk_bf16(v1[2] * silu_f(bflo(gz.w)), v1[3] * silu_f(bfhi(gz.w)));
;                     *(u32x4*)(O + row * DM + coff + col0 + bj * 128) = w; } }
	v_lshlrev_b32_e32 v122, 16, v114
	v_mul_f32_e32 v123, 0xbfb8aa3b, v122
	v_exp_f32_e32 v123, v123
	v_and_b32_e32 v114, 0xffff0000, v114
	v_add_f32_e32 v123, 1.0, v123
	v_div_scale_f32 v124, s[12:13], v123, v123, v122
	v_rcp_f32_e32 v125, v124
	s_nop 0
	v_fma_f32 v126, -v124, v125, 1.0
	v_fmac_f32_e32 v125, v126, v125
	v_div_scale_f32 v126, vcc, v122, v123, v122
	v_mul_f32_e32 v127, v126, v125
	v_fma_f32 v128, -v124, v127, v126
	v_fmac_f32_e32 v127, v128, v125
	v_fma_f32 v124, -v124, v127, v126
	v_div_fmas_f32 v124, v124, v125, v127
	v_div_fixup_f32 v122, v124, v123, v122
	v_mul_f32_e32 v110, v110, v122
	v_mul_f32_e32 v122, 0xbfb8aa3b, v114
	v_exp_f32_e32 v122, v122
	s_nop 0
	v_add_f32_e32 v122, 1.0, v122
	v_div_scale_f32 v123, s[12:13], v122, v122, v114
	v_rcp_f32_e32 v124, v123
	s_nop 0
	v_fma_f32 v125, -v123, v124, 1.0
	v_fmac_f32_e32 v124, v125, v124
	v_div_scale_f32 v125, vcc, v114, v122, v114
	v_mul_f32_e32 v126, v125, v124
	v_fma_f32 v127, -v123, v126, v125
	v_fmac_f32_e32 v126, v127, v124
	v_fma_f32 v123, -v123, v126, v125
	v_div_fmas_f32 v123, v123, v124, v126
	v_div_fixup_f32 v114, v123, v122, v114
	v_mul_f32_e32 v111, v111, v114
	v_cvt_pk_bf16_f32 v110, v110, v111
	v_lshlrev_b32_e32 v111, 16, v115
	v_mul_f32_e32 v114, 0xbfb8aa3b, v111
	v_exp_f32_e32 v114, v114
	s_nop 0
	v_add_f32_e32 v114, 1.0, v114
	v_div_scale_f32 v122, s[12:13], v114, v114, v111
	v_rcp_f32_e32 v123, v122
	s_nop 0
	v_fma_f32 v124, -v122, v123, 1.0
	v_fmac_f32_e32 v123, v124, v123
	v_div_scale_f32 v124, vcc, v111, v114, v111
	v_mul_f32_e32 v125, v124, v123
	v_fma_f32 v126, -v122, v125, v124
	v_fmac_f32_e32 v125, v126, v123
	v_fma_f32 v122, -v122, v125, v124
	v_div_fmas_f32 v122, v122, v123, v125
	v_div_fixup_f32 v111, v122, v114, v111
	v_mul_f32_e32 v111, v112, v111
	v_and_b32_e32 v112, 0xffff0000, v115
	v_mul_f32_e32 v114, 0xbfb8aa3b, v112
	v_exp_f32_e32 v114, v114
	s_nop 0
	v_add_f32_e32 v114, 1.0, v114
	v_div_scale_f32 v115, s[12:13], v114, v114, v112
	v_rcp_f32_e32 v122, v115
	s_nop 0
	v_fma_f32 v123, -v115, v122, 1.0
	v_fmac_f32_e32 v122, v123, v122
	v_div_scale_f32 v123, vcc, v112, v114, v112
	v_mul_f32_e32 v124, v123, v122
	v_fma_f32 v125, -v115, v124, v123
	v_fmac_f32_e32 v124, v125, v122
	v_fma_f32 v115, -v115, v124, v123
	v_div_fmas_f32 v115, v115, v122, v124
	v_div_fixup_f32 v112, v115, v114, v112
	v_mul_f32_e32 v112, v113, v112
	v_cvt_pk_bf16_f32 v111, v111, v112
	v_lshlrev_b32_e32 v112, 16, v116
	v_mul_f32_e32 v113, 0xbfb8aa3b, v112
	v_exp_f32_e32 v113, v113
	s_nop 0
	v_add_f32_e32 v113, 1.0, v113
	v_div_scale_f32 v114, s[12:13], v113, v113, v112
	v_rcp_f32_e32 v115, v114
	s_nop 0
	v_fma_f32 v122, -v114, v115, 1.0
	v_fmac_f32_e32 v115, v122, v115
	v_div_scale_f32 v122, vcc, v112, v113, v112
	v_mul_f32_e32 v123, v122, v115
	v_fma_f32 v124, -v114, v123, v122
	v_fmac_f32_e32 v123, v124, v115
	v_fma_f32 v114, -v114, v123, v122
	v_div_fmas_f32 v114, v114, v115, v123
	v_div_fixup_f32 v112, v114, v113, v112
	v_mul_f32_e32 v106, v106, v112
	v_and_b32_e32 v112, 0xffff0000, v116
	v_mul_f32_e32 v113, 0xbfb8aa3b, v112
	v_exp_f32_e32 v113, v113
	s_nop 0
	v_add_f32_e32 v113, 1.0, v113
	v_div_scale_f32 v114, s[12:13], v113, v113, v112
	v_rcp_f32_e32 v115, v114
	s_nop 0
	v_fma_f32 v116, -v114, v115, 1.0
	v_fmac_f32_e32 v115, v116, v115
	v_div_scale_f32 v116, vcc, v112, v113, v112
	v_mul_f32_e32 v122, v116, v115
	v_fma_f32 v123, -v114, v122, v116
	v_fmac_f32_e32 v122, v123, v115
	v_fma_f32 v114, -v114, v122, v116
	v_div_fmas_f32 v114, v114, v115, v122
	v_div_fixup_f32 v112, v114, v113, v112
	v_mul_f32_e32 v107, v107, v112
	v_cvt_pk_bf16_f32 v112, v106, v107
	v_lshlrev_b32_e32 v106, 16, v117
	v_mul_f32_e32 v107, 0xbfb8aa3b, v106
	v_exp_f32_e32 v107, v107
	s_nop 0
	v_add_f32_e32 v107, 1.0, v107
	v_div_scale_f32 v113, s[12:13], v107, v107, v106
	v_rcp_f32_e32 v114, v113
	s_nop 0
	v_fma_f32 v115, -v113, v114, 1.0
	v_fmac_f32_e32 v114, v115, v114
	v_div_scale_f32 v115, vcc, v106, v107, v106
	v_mul_f32_e32 v116, v115, v114
	v_fma_f32 v122, -v113, v116, v115
	v_fmac_f32_e32 v116, v122, v114
	v_fma_f32 v113, -v113, v116, v115
	v_div_fmas_f32 v113, v113, v114, v116
	v_div_fixup_f32 v106, v113, v107, v106
	v_and_b32_e32 v107, 0xffff0000, v117
	v_mul_f32_e32 v106, v108, v106
	v_mul_f32_e32 v108, 0xbfb8aa3b, v107
	v_exp_f32_e32 v108, v108
	s_nop 0
	v_add_f32_e32 v108, 1.0, v108
	v_div_scale_f32 v113, s[12:13], v108, v108, v107
	v_rcp_f32_e32 v114, v113
	s_nop 0
	v_fma_f32 v115, -v113, v114, 1.0
	v_fmac_f32_e32 v114, v115, v114
	v_div_scale_f32 v115, vcc, v107, v108, v107
	v_mul_f32_e32 v116, v115, v114
	v_fma_f32 v117, -v113, v116, v115
	v_fmac_f32_e32 v116, v117, v114
	v_fma_f32 v113, -v113, v116, v115
	v_div_fmas_f32 v113, v113, v114, v116
	v_div_fixup_f32 v107, v113, v108, v107
	v_mul_f32_e32 v107, v109, v107
	v_cvt_pk_bf16_f32 v113, v106, v107
	v_lshl_add_u64 v[106:107], s[72:73], 0, v[118:119]
	v_lshl_add_u64 v[114:115], v[106:107], 0, v[144:145]
	global_store_dwordx4 v[114:115], v[110:113], off
	global_load_dwordx4 v[106:109], v[120:121], off offset:256
	s_waitcnt vmcnt(0)
; __device__ __forceinline__ unsigned cvt_pk_bf16(float lo, float hi) { unsigned r; asm volatile("v_cvt_pk_bf16_f32 %0, %1, %2" : "=v"(r) : "v"(lo), "v"(hi)); return r; }
; __device__ __forceinline__ float bflo(unsigned u) { return __uint_as_float(u << 16); }
; __device__ __forceinline__ float bfhi(unsigned u) { return __uint_as_float(u & 0xffff0000u); }
; __device__ __forceinline__ float silu_f(float v) { return v / (1.f + __expf(-v)); }
;     __device__ __forceinline__ void operator()(const pg8::f32x4 (&acc)[2][2][4][2], const pg8::Unit& u, int wr, int wc, int fr, int fq) const {
;     ...
;             for (int m = 0; m < 4; ++m) { const size_t row = (size_t)(row0 + ai * 128 + m * 16);
; #pragma unroll
;                 for (int bj = 0; bj < 2; ++bj) { const pg8::f32x4 v0 = acc[ai][bj][m][0], v1 = acc[ai][bj][m][1];
;                     const u32x4 gz = *(const u32x4*)(Z + row * DIN + goff + col0 + bj * 128); u32x4 w;
;                     w.x = pg8::cvt_pk_bf16(v0[0] * silu_f(bflo(gz.x)), v0[1] * silu_f(bfhi(gz.x))); w.y = pg8::cvt_pk_bf16(v0[2] * silu_f(bflo(gz.y)), v0[3] * silu_f(bfhi(gz.y)));
;                     w.z = pg8::cvt_pk_bf16(v1[0] * silu_f(bflo(gz.z)), v1[1] * silu_f(bfhi(gz.z))); w.w = pg8::cvt_pk_bf16(v1[2] * silu_f(bflo(gz.w)), v1[3] * silu_f(bfhi(gz.w)));
;                     *(u32x4*)(O + row * DM + coff + col0 + bj * 128) = w; } }
	v_lshlrev_b32_e32 v110, 16, v106
	v_mul_f32_e32 v111, 0xbfb8aa3b, v110
	v_exp_f32_e32 v111, v111
	v_and_b32_e32 v106, 0xffff0000, v106
	v_add_f32_e32 v111, 1.0, v111
	v_div_scale_f32 v112, s[12:13], v111, v111, v110
	v_rcp_f32_e32 v113, v112
	s_nop 0
	v_fma_f32 v116, -v112, v113, 1.0
	v_fmac_f32_e32 v113, v116, v113
	v_div_scale_f32 v116, vcc, v110, v111, v110
	v_mul_f32_e32 v117, v116, v113
	v_fma_f32 v118, -v112, v117, v116
	v_fmac_f32_e32 v117, v118, v113
	v_fma_f32 v112, -v112, v117, v116
	v_div_fmas_f32 v112, v112, v113, v117
	v_div_fixup_f32 v110, v112, v111, v110
	v_mul_f32_e32 v102, v102, v110
	v_mul_f32_e32 v110, 0xbfb8aa3b, v106
	v_exp_f32_e32 v110, v110
	s_nop 0
	v_add_f32_e32 v110, 1.0, v110
	v_div_scale_f32 v111, s[12:13], v110, v110, v106
	v_rcp_f32_e32 v112, v111
	s_nop 0
	v_fma_f32 v113, -v111, v112, 1.0
	v_fmac_f32_e32 v112, v113, v112
	v_div_scale_f32 v113, vcc, v106, v110, v106
	v_mul_f32_e32 v116, v113, v112
	v_fma_f32 v117, -v111, v116, v113
	v_fmac_f32_e32 v116, v117, v112
	v_fma_f32 v111, -v111, v116, v113
	v_div_fmas_f32 v111, v111, v112, v116
	v_div_fixup_f32 v106, v111, v110, v106
	v_mul_f32_e32 v103, v103, v106
	v_cvt_pk_bf16_f32 v102, v102, v103
	v_lshlrev_b32_e32 v103, 16, v107
	v_mul_f32_e32 v106, 0xbfb8aa3b, v103
	v_exp_f32_e32 v106, v106
	s_nop 0
	v_add_f32_e32 v106, 1.0, v106
	v_div_scale_f32 v110, s[12:13], v106, v106, v103
	v_rcp_f32_e32 v111, v110
	s_nop 0
	v_fma_f32 v112, -v110, v111, 1.0
	v_fmac_f32_e32 v111, v112, v111
	v_div_scale_f32 v112, vcc, v103, v106, v103
	v_mul_f32_e32 v113, v112, v111
	v_fma_f32 v116, -v110, v113, v112
	v_fmac_f32_e32 v113, v116, v111
	v_fma_f32 v110, -v110, v113, v112
	v_div_fmas_f32 v110, v110, v111, v113
	v_div_fixup_f32 v103, v110, v106, v103
	v_mul_f32_e32 v103, v104, v103
	v_and_b32_e32 v104, 0xffff0000, v107
	v_mul_f32_e32 v106, 0xbfb8aa3b, v104
	v_exp_f32_e32 v106, v106
	s_nop 0
	v_add_f32_e32 v106, 1.0, v106
	v_div_scale_f32 v107, s[12:13], v106, v106, v104
	v_rcp_f32_e32 v110, v107
	s_nop 0
	v_fma_f32 v111, -v107, v110, 1.0
	v_fmac_f32_e32 v110, v111, v110
	v_div_scale_f32 v111, vcc, v104, v106, v104
	v_mul_f32_e32 v112, v111, v110
	v_fma_f32 v113, -v107, v112, v111
	v_fmac_f32_e32 v112, v113, v110
	v_fma_f32 v107, -v107, v112, v111
	v_div_fmas_f32 v107, v107, v110, v112
	v_div_fixup_f32 v104, v107, v106, v104
	v_mul_f32_e32 v104, v105, v104
	v_cvt_pk_bf16_f32 v103, v103, v104
	v_lshlrev_b32_e32 v104, 16, v108
	v_mul_f32_e32 v105, 0xbfb8aa3b, v104
	v_exp_f32_e32 v105, v105
	s_nop 0
	v_add_f32_e32 v105, 1.0, v105
	v_div_scale_f32 v106, s[12:13], v105, v105, v104
	v_rcp_f32_e32 v107, v106
	s_nop 0
	v_fma_f32 v110, -v106, v107, 1.0
	v_fmac_f32_e32 v107, v110, v107
	v_div_scale_f32 v110, vcc, v104, v105, v104
	v_mul_f32_e32 v111, v110, v107
	v_fma_f32 v112, -v106, v111, v110
	v_fmac_f32_e32 v111, v112, v107
	v_fma_f32 v106, -v106, v111, v110
	v_div_fmas_f32 v106, v106, v107, v111
	v_div_fixup_f32 v104, v106, v105, v104
	v_mul_f32_e32 v98, v98, v104
	v_and_b32_e32 v104, 0xffff0000, v108
	v_mul_f32_e32 v105, 0xbfb8aa3b, v104
	v_exp_f32_e32 v105, v105
	s_nop 0
	v_add_f32_e32 v105, 1.0, v105
	v_div_scale_f32 v106, s[12:13], v105, v105, v104
	v_rcp_f32_e32 v107, v106
	s_nop 0
	v_fma_f32 v108, -v106, v107, 1.0
	v_fmac_f32_e32 v107, v108, v107
	v_div_scale_f32 v108, vcc, v104, v105, v104
	v_mul_f32_e32 v110, v108, v107
	v_fma_f32 v111, -v106, v110, v108
	v_fmac_f32_e32 v110, v111, v107
	v_fma_f32 v106, -v106, v110, v108
	v_div_fmas_f32 v106, v106, v107, v110
	v_div_fixup_f32 v104, v106, v105, v104
	v_mul_f32_e32 v99, v99, v104
	v_cvt_pk_bf16_f32 v104, v98, v99
	v_lshlrev_b32_e32 v98, 16, v109
	v_mul_f32_e32 v99, 0xbfb8aa3b, v98
	v_exp_f32_e32 v99, v99
	s_nop 0
	v_add_f32_e32 v99, 1.0, v99
	v_div_scale_f32 v105, s[12:13], v99, v99, v98
	v_rcp_f32_e32 v106, v105
	s_nop 0
	v_fma_f32 v107, -v105, v106, 1.0
	v_fmac_f32_e32 v106, v107, v106
	v_div_scale_f32 v107, vcc, v98, v99, v98
	v_mul_f32_e32 v108, v107, v106
	v_fma_f32 v110, -v105, v108, v107
	v_fmac_f32_e32 v108, v110, v106
	v_fma_f32 v105, -v105, v108, v107
	v_div_fmas_f32 v105, v105, v106, v108
	v_div_fixup_f32 v98, v105, v99, v98
	v_and_b32_e32 v99, 0xffff0000, v109
	v_mul_f32_e32 v98, v100, v98
	v_mul_f32_e32 v100, 0xbfb8aa3b, v99
	v_exp_f32_e32 v100, v100
	s_nop 0
	v_add_f32_e32 v100, 1.0, v100
	v_div_scale_f32 v105, s[12:13], v100, v100, v99
	v_rcp_f32_e32 v106, v105
	s_nop 0
	v_fma_f32 v107, -v105, v106, 1.0
	v_fmac_f32_e32 v106, v107, v106
	v_div_scale_f32 v107, vcc, v99, v100, v99
	v_mul_f32_e32 v108, v107, v106
	v_fma_f32 v109, -v105, v108, v107
	v_fmac_f32_e32 v108, v109, v106
	v_fma_f32 v105, -v105, v108, v107
	v_div_fmas_f32 v105, v105, v106, v108
	v_div_fixup_f32 v99, v105, v100, v99
	v_mul_f32_e32 v99, v101, v99
	v_cvt_pk_bf16_f32 v105, v98, v99
	v_or_b32_e32 v98, 32, v160
	v_ashrrev_i32_e32 v99, 31, v98
	global_store_dwordx4 v[114:115], v[102:105], off offset:256
	s_nop 1
	v_lshlrev_b64 v[102:103], 12, v[98:99]
	v_mad_i64_i32 v[98:99], s[12:13], v98, s75, v[162:163]
	v_lshl_add_u64 v[98:99], v[98:99], 0, v[144:145]
	v_lshl_add_u64 v[104:105], v[98:99], 0, s[26:27]
	v_add_co_u32_e32 v98, vcc, s5, v98
	s_nop 1
	v_addc_co_u32_e32 v99, vcc, 0, v99, vcc
	global_load_dwordx4 v[98:101], v[98:99], off
	s_waitcnt vmcnt(0)
; __device__ __forceinline__ unsigned cvt_pk_bf16(float lo, float hi) { unsigned r; asm volatile("v_cvt_pk_bf16_f32 %0, %1, %2" : "=v"(r) : "v"(lo), "v"(hi)); return r; }
; __device__ __forceinline__ float bflo(unsigned u) { return __uint_as_float(u << 16); }
; __device__ __forceinline__ float bfhi(unsigned u) { return __uint_as_float(u & 0xffff0000u); }
; __device__ __forceinline__ float silu_f(float v) { return v / (1.f + __expf(-v)); }
;     __device__ __forceinline__ void operator()(const pg8::f32x4 (&acc)[2][2][4][2], const pg8::Unit& u, int wr, int wc, int fr, int fq) const {
;     ...
;             for (int m = 0; m < 4; ++m) { const size_t row = (size_t)(row0 + ai * 128 + m * 16);
; #pragma unroll
;                 for (int bj = 0; bj < 2; ++bj) { const pg8::f32x4 v0 = acc[ai][bj][m][0], v1 = acc[ai][bj][m][1];
;                     const u32x4 gz = *(const u32x4*)(Z + row * DIN + goff + col0 + bj * 128); u32x4 w;
;                     w.x = pg8::cvt_pk_bf16(v0[0] * silu_f(bflo(gz.x)), v0[1] * silu_f(bfhi(gz.x))); w.y = pg8::cvt_pk_bf16(v0[2] * silu_f(bflo(gz.y)), v0[3] * silu_f(bfhi(gz.y)));
;                     w.z = pg8::cvt_pk_bf16(v1[0] * silu_f(bflo(gz.z)), v1[1] * silu_f(bfhi(gz.z))); w.w = pg8::cvt_pk_bf16(v1[2] * silu_f(bflo(gz.w)), v1[3] * silu_f(bfhi(gz.w)));
;                     *(u32x4*)(O + row * DM + coff + col0 + bj * 128) = w; } }
	v_lshlrev_b32_e32 v106, 16, v98
	v_mul_f32_e32 v107, 0xbfb8aa3b, v106
	v_exp_f32_e32 v107, v107
	v_and_b32_e32 v98, 0xffff0000, v98
	v_add_f32_e32 v107, 1.0, v107
	v_div_scale_f32 v108, s[12:13], v107, v107, v106
	v_rcp_f32_e32 v109, v108
	s_nop 0
	v_fma_f32 v110, -v108, v109, 1.0
	v_fmac_f32_e32 v109, v110, v109
	v_div_scale_f32 v110, vcc, v106, v107, v106
	v_mul_f32_e32 v111, v110, v109
	v_fma_f32 v112, -v108, v111, v110
	v_fmac_f32_e32 v111, v112, v109
	v_fma_f32 v108, -v108, v111, v110
	v_div_fmas_f32 v108, v108, v109, v111
	v_div_fixup_f32 v106, v108, v107, v106
	v_mul_f32_e32 v94, v94, v106
	v_mul_f32_e32 v106, 0xbfb8aa3b, v98
	v_exp_f32_e32 v106, v106
	s_nop 0
	v_add_f32_e32 v106, 1.0, v106
	v_div_scale_f32 v107, s[12:13], v106, v106, v98
	v_rcp_f32_e32 v108, v107
	s_nop 0
	v_fma_f32 v109, -v107, v108, 1.0
	v_fmac_f32_e32 v108, v109, v108
	v_div_scale_f32 v109, vcc, v98, v106, v98
	v_mul_f32_e32 v110, v109, v108
	v_fma_f32 v111, -v107, v110, v109
	v_fmac_f32_e32 v110, v111, v108
	v_fma_f32 v107, -v107, v110, v109
	v_div_fmas_f32 v107, v107, v108, v110
	v_div_fixup_f32 v98, v107, v106, v98
	v_mul_f32_e32 v95, v95, v98
	v_cvt_pk_bf16_f32 v94, v94, v95
	v_lshlrev_b32_e32 v95, 16, v99
	v_mul_f32_e32 v98, 0xbfb8aa3b, v95
	v_exp_f32_e32 v98, v98
	s_nop 0
	v_add_f32_e32 v98, 1.0, v98
	v_div_scale_f32 v106, s[12:13], v98, v98, v95
	v_rcp_f32_e32 v107, v106
	s_nop 0
	v_fma_f32 v108, -v106, v107, 1.0
	v_fmac_f32_e32 v107, v108, v107
	v_div_scale_f32 v108, vcc, v95, v98, v95
	v_mul_f32_e32 v109, v108, v107
	v_fma_f32 v110, -v106, v109, v108
	v_fmac_f32_e32 v109, v110, v107
	v_fma_f32 v106, -v106, v109, v108
	v_div_fmas_f32 v106, v106, v107, v109
	v_div_fixup_f32 v95, v106, v98, v95
	v_mul_f32_e32 v95, v96, v95
	v_and_b32_e32 v96, 0xffff0000, v99
	v_mul_f32_e32 v98, 0xbfb8aa3b, v96
	v_exp_f32_e32 v98, v98
	s_nop 0
	v_add_f32_e32 v98, 1.0, v98
	v_div_scale_f32 v99, s[12:13], v98, v98, v96
	v_rcp_f32_e32 v106, v99
	s_nop 0
	v_fma_f32 v107, -v99, v106, 1.0
	v_fmac_f32_e32 v106, v107, v106
	v_div_scale_f32 v107, vcc, v96, v98, v96
	v_mul_f32_e32 v108, v107, v106
	v_fma_f32 v109, -v99, v108, v107
	v_fmac_f32_e32 v108, v109, v106
	v_fma_f32 v99, -v99, v108, v107
	v_div_fmas_f32 v99, v99, v106, v108
	v_div_fixup_f32 v96, v99, v98, v96
	v_mul_f32_e32 v96, v97, v96
	v_cvt_pk_bf16_f32 v95, v95, v96
	v_lshlrev_b32_e32 v96, 16, v100
	v_mul_f32_e32 v97, 0xbfb8aa3b, v96
	v_exp_f32_e32 v97, v97
	s_nop 0
	v_add_f32_e32 v97, 1.0, v97
	v_div_scale_f32 v98, s[12:13], v97, v97, v96
	v_rcp_f32_e32 v99, v98
	s_nop 0
	v_fma_f32 v106, -v98, v99, 1.0
	v_fmac_f32_e32 v99, v106, v99
	v_div_scale_f32 v106, vcc, v96, v97, v96
	v_mul_f32_e32 v107, v106, v99
	v_fma_f32 v108, -v98, v107, v106
	v_fmac_f32_e32 v107, v108, v99
	v_fma_f32 v98, -v98, v107, v106
	v_div_fmas_f32 v98, v98, v99, v107
	v_div_fixup_f32 v96, v98, v97, v96
	v_mul_f32_e32 v90, v90, v96
	v_and_b32_e32 v96, 0xffff0000, v100
	v_mul_f32_e32 v97, 0xbfb8aa3b, v96
	v_exp_f32_e32 v97, v97
	s_nop 0
	v_add_f32_e32 v97, 1.0, v97
	v_div_scale_f32 v98, s[12:13], v97, v97, v96
	v_rcp_f32_e32 v99, v98
	s_nop 0
	v_fma_f32 v100, -v98, v99, 1.0
	v_fmac_f32_e32 v99, v100, v99
	v_div_scale_f32 v100, vcc, v96, v97, v96
	v_mul_f32_e32 v106, v100, v99
	v_fma_f32 v107, -v98, v106, v100
	v_fmac_f32_e32 v106, v107, v99
	v_fma_f32 v98, -v98, v106, v100
	v_div_fmas_f32 v98, v98, v99, v106
	v_div_fixup_f32 v96, v98, v97, v96
	v_mul_f32_e32 v91, v91, v96
	v_cvt_pk_bf16_f32 v96, v90, v91
	v_lshlrev_b32_e32 v90, 16, v101
	v_mul_f32_e32 v91, 0xbfb8aa3b, v90
	v_exp_f32_e32 v91, v91
	s_nop 0
	v_add_f32_e32 v91, 1.0, v91
	v_div_scale_f32 v97, s[12:13], v91, v91, v90
	v_rcp_f32_e32 v98, v97
	s_nop 0
	v_fma_f32 v99, -v97, v98, 1.0
	v_fmac_f32_e32 v98, v99, v98
	v_div_scale_f32 v99, vcc, v90, v91, v90
	v_mul_f32_e32 v100, v99, v98
	v_fma_f32 v106, -v97, v100, v99
	v_fmac_f32_e32 v100, v106, v98
	v_fma_f32 v97, -v97, v100, v99
	v_div_fmas_f32 v97, v97, v98, v100
	v_div_fixup_f32 v90, v97, v91, v90
	v_and_b32_e32 v91, 0xffff0000, v101
	v_mul_f32_e32 v90, v92, v90
	v_mul_f32_e32 v92, 0xbfb8aa3b, v91
	v_exp_f32_e32 v92, v92
	s_nop 0
	v_add_f32_e32 v92, 1.0, v92
	v_div_scale_f32 v97, s[12:13], v92, v92, v91
	v_rcp_f32_e32 v98, v97
	s_nop 0
	v_fma_f32 v99, -v97, v98, 1.0
	v_fmac_f32_e32 v98, v99, v98
	v_div_scale_f32 v99, vcc, v91, v92, v91
	v_mul_f32_e32 v100, v99, v98
	v_fma_f32 v101, -v97, v100, v99
	v_fmac_f32_e32 v100, v101, v98
	v_fma_f32 v97, -v97, v100, v99
	v_div_fmas_f32 v97, v97, v98, v100
	v_div_fixup_f32 v91, v97, v92, v91
	v_mul_f32_e32 v91, v93, v91
	v_cvt_pk_bf16_f32 v97, v90, v91
	v_lshl_add_u64 v[90:91], s[72:73], 0, v[102:103]
	v_lshl_add_u64 v[98:99], v[90:91], 0, v[144:145]
	global_store_dwordx4 v[98:99], v[94:97], off
	global_load_dwordx4 v[90:93], v[104:105], off offset:256
	s_waitcnt vmcnt(0)
; __device__ __forceinline__ unsigned cvt_pk_bf16(float lo, float hi) { unsigned r; asm volatile("v_cvt_pk_bf16_f32 %0, %1, %2" : "=v"(r) : "v"(lo), "v"(hi)); return r; }
; __device__ __forceinline__ float bflo(unsigned u) { return __uint_as_float(u << 16); }
; __device__ __forceinline__ float bfhi(unsigned u) { return __uint_as_float(u & 0xffff0000u); }
; __device__ __forceinline__ float silu_f(float v) { return v / (1.f + __expf(-v)); }
;     __device__ __forceinline__ void operator()(const pg8::f32x4 (&acc)[2][2][4][2], const pg8::Unit& u, int wr, int wc, int fr, int fq) const {
;     ...
;             for (int m = 0; m < 4; ++m) { const size_t row = (size_t)(row0 + ai * 128 + m * 16);
; #pragma unroll
;                 for (int bj = 0; bj < 2; ++bj) { const pg8::f32x4 v0 = acc[ai][bj][m][0], v1 = acc[ai][bj][m][1];
;                     const u32x4 gz = *(const u32x4*)(Z + row * DIN + goff + col0 + bj * 128); u32x4 w;
;                     w.x = pg8::cvt_pk_bf16(v0[0] * silu_f(bflo(gz.x)), v0[1] * silu_f(bfhi(gz.x))); w.y = pg8::cvt_pk_bf16(v0[2] * silu_f(bflo(gz.y)), v0[3] * silu_f(bfhi(gz.y)));
;                     w.z = pg8::cvt_pk_bf16(v1[0] * silu_f(bflo(gz.z)), v1[1] * silu_f(bfhi(gz.z))); w.w = pg8::cvt_pk_bf16(v1[2] * silu_f(bflo(gz.w)), v1[3] * silu_f(bfhi(gz.w)));
;                     *(u32x4*)(O + row * DM + coff + col0 + bj * 128) = w; } }
	v_lshlrev_b32_e32 v94, 16, v90
	v_mul_f32_e32 v95, 0xbfb8aa3b, v94
	v_exp_f32_e32 v95, v95
	v_and_b32_e32 v90, 0xffff0000, v90
	v_add_f32_e32 v95, 1.0, v95
	v_div_scale_f32 v96, s[12:13], v95, v95, v94
	v_rcp_f32_e32 v97, v96
	s_nop 0
	v_fma_f32 v100, -v96, v97, 1.0
	v_fmac_f32_e32 v97, v100, v97
	v_div_scale_f32 v100, vcc, v94, v95, v94
	v_mul_f32_e32 v101, v100, v97
	v_fma_f32 v102, -v96, v101, v100
	v_fmac_f32_e32 v101, v102, v97
	v_fma_f32 v96, -v96, v101, v100
	v_div_fmas_f32 v96, v96, v97, v101
	v_div_fixup_f32 v94, v96, v95, v94
	v_mul_f32_e32 v86, v86, v94
	v_mul_f32_e32 v94, 0xbfb8aa3b, v90
	v_exp_f32_e32 v94, v94
	s_nop 0
	v_add_f32_e32 v94, 1.0, v94
	v_div_scale_f32 v95, s[12:13], v94, v94, v90
	v_rcp_f32_e32 v96, v95
	s_nop 0
	v_fma_f32 v97, -v95, v96, 1.0
	v_fmac_f32_e32 v96, v97, v96
	v_div_scale_f32 v97, vcc, v90, v94, v90
	v_mul_f32_e32 v100, v97, v96
	v_fma_f32 v101, -v95, v100, v97
	v_fmac_f32_e32 v100, v101, v96
	v_fma_f32 v95, -v95, v100, v97
	v_div_fmas_f32 v95, v95, v96, v100
	v_div_fixup_f32 v90, v95, v94, v90
	v_mul_f32_e32 v87, v87, v90
	v_cvt_pk_bf16_f32 v86, v86, v87
	v_lshlrev_b32_e32 v87, 16, v91
	v_mul_f32_e32 v90, 0xbfb8aa3b, v87
	v_exp_f32_e32 v90, v90
	s_nop 0
	v_add_f32_e32 v90, 1.0, v90
	v_div_scale_f32 v94, s[12:13], v90, v90, v87
	v_rcp_f32_e32 v95, v94
	s_nop 0
	v_fma_f32 v96, -v94, v95, 1.0
	v_fmac_f32_e32 v95, v96, v95
	v_div_scale_f32 v96, vcc, v87, v90, v87
	v_mul_f32_e32 v97, v96, v95
	v_fma_f32 v100, -v94, v97, v96
	v_fmac_f32_e32 v97, v100, v95
	v_fma_f32 v94, -v94, v97, v96
	v_div_fmas_f32 v94, v94, v95, v97
	v_div_fixup_f32 v87, v94, v90, v87
	v_mul_f32_e32 v87, v88, v87
	v_and_b32_e32 v88, 0xffff0000, v91
	v_mul_f32_e32 v90, 0xbfb8aa3b, v88
	v_exp_f32_e32 v90, v90
	s_nop 0
	v_add_f32_e32 v90, 1.0, v90
	v_div_scale_f32 v91, s[12:13], v90, v90, v88
	v_rcp_f32_e32 v94, v91
	s_nop 0
	v_fma_f32 v95, -v91, v94, 1.0
	v_fmac_f32_e32 v94, v95, v94
	v_div_scale_f32 v95, vcc, v88, v90, v88
	v_mul_f32_e32 v96, v95, v94
	v_fma_f32 v97, -v91, v96, v95
	v_fmac_f32_e32 v96, v97, v94
	v_fma_f32 v91, -v91, v96, v95
	v_div_fmas_f32 v91, v91, v94, v96
	v_div_fixup_f32 v88, v91, v90, v88
	v_mul_f32_e32 v88, v89, v88
	v_cvt_pk_bf16_f32 v87, v87, v88
	v_lshlrev_b32_e32 v88, 16, v92
	v_mul_f32_e32 v89, 0xbfb8aa3b, v88
	v_exp_f32_e32 v89, v89
	s_nop 0
	v_add_f32_e32 v89, 1.0, v89
	v_div_scale_f32 v90, s[12:13], v89, v89, v88
	v_rcp_f32_e32 v91, v90
	s_nop 0
	v_fma_f32 v94, -v90, v91, 1.0
	v_fmac_f32_e32 v91, v94, v91
	v_div_scale_f32 v94, vcc, v88, v89, v88
	v_mul_f32_e32 v95, v94, v91
	v_fma_f32 v96, -v90, v95, v94
	v_fmac_f32_e32 v95, v96, v91
	v_fma_f32 v90, -v90, v95, v94
	v_div_fmas_f32 v90, v90, v91, v95
	v_div_fixup_f32 v88, v90, v89, v88
	v_mul_f32_e32 v82, v82, v88
	v_and_b32_e32 v88, 0xffff0000, v92
	v_mul_f32_e32 v89, 0xbfb8aa3b, v88
	v_exp_f32_e32 v89, v89
	s_nop 0
	v_add_f32_e32 v89, 1.0, v89
	v_div_scale_f32 v90, s[12:13], v89, v89, v88
	v_rcp_f32_e32 v91, v90
	s_nop 0
	v_fma_f32 v92, -v90, v91, 1.0
	v_fmac_f32_e32 v91, v92, v91
	v_div_scale_f32 v92, vcc, v88, v89, v88
	v_mul_f32_e32 v94, v92, v91
	v_fma_f32 v95, -v90, v94, v92
	v_fmac_f32_e32 v94, v95, v91
	v_fma_f32 v90, -v90, v94, v92
	v_div_fmas_f32 v90, v90, v91, v94
	v_div_fixup_f32 v88, v90, v89, v88
	v_mul_f32_e32 v83, v83, v88
	v_cvt_pk_bf16_f32 v88, v82, v83
	v_lshlrev_b32_e32 v82, 16, v93
	v_mul_f32_e32 v83, 0xbfb8aa3b, v82
	v_exp_f32_e32 v83, v83
	s_nop 0
	v_add_f32_e32 v83, 1.0, v83
	v_div_scale_f32 v89, s[12:13], v83, v83, v82
	v_rcp_f32_e32 v90, v89
	s_nop 0
	v_fma_f32 v91, -v89, v90, 1.0
	v_fmac_f32_e32 v90, v91, v90
	v_div_scale_f32 v91, vcc, v82, v83, v82
	v_mul_f32_e32 v92, v91, v90
	v_fma_f32 v94, -v89, v92, v91
	v_fmac_f32_e32 v92, v94, v90
	v_fma_f32 v89, -v89, v92, v91
	v_div_fmas_f32 v89, v89, v90, v92
	v_div_fixup_f32 v82, v89, v83, v82
	v_and_b32_e32 v83, 0xffff0000, v93
	v_mul_f32_e32 v82, v84, v82
	v_mul_f32_e32 v84, 0xbfb8aa3b, v83
	v_exp_f32_e32 v84, v84
	s_nop 0
	v_add_f32_e32 v84, 1.0, v84
	v_div_scale_f32 v89, s[12:13], v84, v84, v83
	v_rcp_f32_e32 v90, v89
	s_nop 0
	v_fma_f32 v91, -v89, v90, 1.0
	v_fmac_f32_e32 v90, v91, v90
	v_div_scale_f32 v91, vcc, v83, v84, v83
	v_mul_f32_e32 v92, v91, v90
	v_fma_f32 v93, -v89, v92, v91
	v_fmac_f32_e32 v92, v93, v90
	v_fma_f32 v89, -v89, v92, v91
	v_div_fmas_f32 v89, v89, v90, v92
	v_div_fixup_f32 v83, v89, v84, v83
	v_mul_f32_e32 v83, v85, v83
	v_cvt_pk_bf16_f32 v89, v82, v83
	v_or_b32_e32 v82, 48, v160
	v_ashrrev_i32_e32 v83, 31, v82
	global_store_dwordx4 v[98:99], v[86:89], off offset:256
	s_nop 1
	v_lshlrev_b64 v[86:87], 12, v[82:83]
	v_mad_i64_i32 v[82:83], s[12:13], v82, s75, v[162:163]
	v_lshl_add_u64 v[82:83], v[82:83], 0, v[144:145]
	v_lshl_add_u64 v[88:89], v[82:83], 0, s[26:27]
	v_add_co_u32_e32 v82, vcc, s5, v82
	s_nop 1
	v_addc_co_u32_e32 v83, vcc, 0, v83, vcc
	global_load_dwordx4 v[82:85], v[82:83], off
	s_waitcnt vmcnt(0)
; __device__ __forceinline__ unsigned cvt_pk_bf16(float lo, float hi) { unsigned r; asm volatile("v_cvt_pk_bf16_f32 %0, %1, %2" : "=v"(r) : "v"(lo), "v"(hi)); return r; }
; __device__ __forceinline__ float bflo(unsigned u) { return __uint_as_float(u << 16); }
; __device__ __forceinline__ float bfhi(unsigned u) { return __uint_as_float(u & 0xffff0000u); }
; __device__ __forceinline__ float silu_f(float v) { return v / (1.f + __expf(-v)); }
;     __device__ __forceinline__ void operator()(const pg8::f32x4 (&acc)[2][2][4][2], const pg8::Unit& u, int wr, int wc, int fr, int fq) const {
;     ...
;             for (int m = 0; m < 4; ++m) { const size_t row = (size_t)(row0 + ai * 128 + m * 16);
; #pragma unroll
;                 for (int bj = 0; bj < 2; ++bj) { const pg8::f32x4 v0 = acc[ai][bj][m][0], v1 = acc[ai][bj][m][1];
;                     const u32x4 gz = *(const u32x4*)(Z + row * DIN + goff + col0 + bj * 128); u32x4 w;
;                     w.x = pg8::cvt_pk_bf16(v0[0] * silu_f(bflo(gz.x)), v0[1] * silu_f(bfhi(gz.x))); w.y = pg8::cvt_pk_bf16(v0[2] * silu_f(bflo(gz.y)), v0[3] * silu_f(bfhi(gz.y)));
;                     w.z = pg8::cvt_pk_bf16(v1[0] * silu_f(bflo(gz.z)), v1[1] * silu_f(bfhi(gz.z))); w.w = pg8::cvt_pk_bf16(v1[2] * silu_f(bflo(gz.w)), v1[3] * silu_f(bfhi(gz.w)));
;                     *(u32x4*)(O + row * DM + coff + col0 + bj * 128) = w; } }
	v_lshlrev_b32_e32 v90, 16, v82
	v_mul_f32_e32 v91, 0xbfb8aa3b, v90
	v_exp_f32_e32 v91, v91
	v_and_b32_e32 v82, 0xffff0000, v82
	v_add_f32_e32 v91, 1.0, v91
	v_div_scale_f32 v92, s[12:13], v91, v91, v90
	v_rcp_f32_e32 v93, v92
	s_nop 0
	v_fma_f32 v94, -v92, v93, 1.0
	v_fmac_f32_e32 v93, v94, v93
	v_div_scale_f32 v94, vcc, v90, v91, v90
	v_mul_f32_e32 v95, v94, v93
	v_fma_f32 v96, -v92, v95, v94
	v_fmac_f32_e32 v95, v96, v93
	v_fma_f32 v92, -v92, v95, v94
	v_div_fmas_f32 v92, v92, v93, v95
	v_div_fixup_f32 v90, v92, v91, v90
	v_mul_f32_e32 v78, v78, v90
	v_mul_f32_e32 v90, 0xbfb8aa3b, v82
	v_exp_f32_e32 v90, v90
	s_nop 0
	v_add_f32_e32 v90, 1.0, v90
	v_div_scale_f32 v91, s[12:13], v90, v90, v82
	v_rcp_f32_e32 v92, v91
	s_nop 0
	v_fma_f32 v93, -v91, v92, 1.0
	v_fmac_f32_e32 v92, v93, v92
	v_div_scale_f32 v93, vcc, v82, v90, v82
	v_mul_f32_e32 v94, v93, v92
	v_fma_f32 v95, -v91, v94, v93
	v_fmac_f32_e32 v94, v95, v92
	v_fma_f32 v91, -v91, v94, v93
	v_div_fmas_f32 v91, v91, v92, v94
	v_div_fixup_f32 v82, v91, v90, v82
	v_mul_f32_e32 v79, v79, v82
	v_cvt_pk_bf16_f32 v78, v78, v79
	v_lshlrev_b32_e32 v79, 16, v83
	v_mul_f32_e32 v82, 0xbfb8aa3b, v79
	v_exp_f32_e32 v82, v82
	s_nop 0
	v_add_f32_e32 v82, 1.0, v82
	v_div_scale_f32 v90, s[12:13], v82, v82, v79
	v_rcp_f32_e32 v91, v90
	s_nop 0
	v_fma_f32 v92, -v90, v91, 1.0
	v_fmac_f32_e32 v91, v92, v91
	v_div_scale_f32 v92, vcc, v79, v82, v79
	v_mul_f32_e32 v93, v92, v91
	v_fma_f32 v94, -v90, v93, v92
	v_fmac_f32_e32 v93, v94, v91
	v_fma_f32 v90, -v90, v93, v92
	v_div_fmas_f32 v90, v90, v91, v93
	v_div_fixup_f32 v79, v90, v82, v79
	v_mul_f32_e32 v79, v80, v79
	v_and_b32_e32 v80, 0xffff0000, v83
	v_mul_f32_e32 v82, 0xbfb8aa3b, v80
	v_exp_f32_e32 v82, v82
	s_nop 0
	v_add_f32_e32 v82, 1.0, v82
	v_div_scale_f32 v83, s[12:13], v82, v82, v80
	v_rcp_f32_e32 v90, v83
	s_nop 0
	v_fma_f32 v91, -v83, v90, 1.0
	v_fmac_f32_e32 v90, v91, v90
	v_div_scale_f32 v91, vcc, v80, v82, v80
	v_mul_f32_e32 v92, v91, v90
	v_fma_f32 v93, -v83, v92, v91
	v_fmac_f32_e32 v92, v93, v90
	v_fma_f32 v83, -v83, v92, v91
	v_div_fmas_f32 v83, v83, v90, v92
	v_div_fixup_f32 v80, v83, v82, v80
	v_mul_f32_e32 v80, v81, v80
	v_cvt_pk_bf16_f32 v79, v79, v80
	v_lshlrev_b32_e32 v80, 16, v84
	v_mul_f32_e32 v81, 0xbfb8aa3b, v80
	v_exp_f32_e32 v81, v81
	s_nop 0
	v_add_f32_e32 v81, 1.0, v81
	v_div_scale_f32 v82, s[12:13], v81, v81, v80
	v_rcp_f32_e32 v83, v82
	s_nop 0
	v_fma_f32 v90, -v82, v83, 1.0
	v_fmac_f32_e32 v83, v90, v83
	v_div_scale_f32 v90, vcc, v80, v81, v80
	v_mul_f32_e32 v91, v90, v83
	v_fma_f32 v92, -v82, v91, v90
	v_fmac_f32_e32 v91, v92, v83
	v_fma_f32 v82, -v82, v91, v90
	v_div_fmas_f32 v82, v82, v83, v91
	v_div_fixup_f32 v80, v82, v81, v80
	v_mul_f32_e32 v74, v74, v80
	v_and_b32_e32 v80, 0xffff0000, v84
	v_mul_f32_e32 v81, 0xbfb8aa3b, v80
	v_exp_f32_e32 v81, v81
	s_nop 0
	v_add_f32_e32 v81, 1.0, v81
	v_div_scale_f32 v82, s[12:13], v81, v81, v80
	v_rcp_f32_e32 v83, v82
	s_nop 0
	v_fma_f32 v84, -v82, v83, 1.0
	v_fmac_f32_e32 v83, v84, v83
	v_div_scale_f32 v84, vcc, v80, v81, v80
	v_mul_f32_e32 v90, v84, v83
	v_fma_f32 v91, -v82, v90, v84
	v_fmac_f32_e32 v90, v91, v83
	v_fma_f32 v82, -v82, v90, v84
	v_div_fmas_f32 v82, v82, v83, v90
	v_div_fixup_f32 v80, v82, v81, v80
	v_mul_f32_e32 v75, v75, v80
	v_cvt_pk_bf16_f32 v80, v74, v75
	v_lshlrev_b32_e32 v74, 16, v85
	v_mul_f32_e32 v75, 0xbfb8aa3b, v74
	v_exp_f32_e32 v75, v75
	s_nop 0
	v_add_f32_e32 v75, 1.0, v75
	v_div_scale_f32 v81, s[12:13], v75, v75, v74
	v_rcp_f32_e32 v82, v81
	s_nop 0
	v_fma_f32 v83, -v81, v82, 1.0
	v_fmac_f32_e32 v82, v83, v82
	v_div_scale_f32 v83, vcc, v74, v75, v74
	v_mul_f32_e32 v84, v83, v82
	v_fma_f32 v90, -v81, v84, v83
	v_fmac_f32_e32 v84, v90, v82
	v_fma_f32 v81, -v81, v84, v83
	v_div_fmas_f32 v81, v81, v82, v84
	v_div_fixup_f32 v74, v81, v75, v74
	v_and_b32_e32 v75, 0xffff0000, v85
	v_mul_f32_e32 v74, v76, v74
	v_mul_f32_e32 v76, 0xbfb8aa3b, v75
	v_exp_f32_e32 v76, v76
	s_nop 0
	v_add_f32_e32 v76, 1.0, v76
	v_div_scale_f32 v81, s[12:13], v76, v76, v75
	v_rcp_f32_e32 v82, v81
	s_nop 0
	v_fma_f32 v83, -v81, v82, 1.0
	v_fmac_f32_e32 v82, v83, v82
	v_div_scale_f32 v83, vcc, v75, v76, v75
	v_mul_f32_e32 v84, v83, v82
	v_fma_f32 v85, -v81, v84, v83
	v_fmac_f32_e32 v84, v85, v82
	v_fma_f32 v81, -v81, v84, v83
	v_div_fmas_f32 v81, v81, v82, v84
	v_div_fixup_f32 v75, v81, v76, v75
	v_mul_f32_e32 v75, v77, v75
	v_cvt_pk_bf16_f32 v81, v74, v75
	v_lshl_add_u64 v[74:75], s[72:73], 0, v[86:87]
	v_lshl_add_u64 v[82:83], v[74:75], 0, v[144:145]
	global_store_dwordx4 v[82:83], v[78:81], off
	global_load_dwordx4 v[74:77], v[88:89], off offset:256
	s_waitcnt vmcnt(0)
; __device__ __forceinline__ unsigned cvt_pk_bf16(float lo, float hi) { unsigned r; asm volatile("v_cvt_pk_bf16_f32 %0, %1, %2" : "=v"(r) : "v"(lo), "v"(hi)); return r; }
; __device__ __forceinline__ float bflo(unsigned u) { return __uint_as_float(u << 16); }
; __device__ __forceinline__ float bfhi(unsigned u) { return __uint_as_float(u & 0xffff0000u); }
; __device__ __forceinline__ float silu_f(float v) { return v / (1.f + __expf(-v)); }
;     __device__ __forceinline__ void operator()(const pg8::f32x4 (&acc)[2][2][4][2], const pg8::Unit& u, int wr, int wc, int fr, int fq) const {
;     ...
;             for (int m = 0; m < 4; ++m) { const size_t row = (size_t)(row0 + ai * 128 + m * 16);
; #pragma unroll
;                 for (int bj = 0; bj < 2; ++bj) { const pg8::f32x4 v0 = acc[ai][bj][m][0], v1 = acc[ai][bj][m][1];
;                     const u32x4 gz = *(const u32x4*)(Z + row * DIN + goff + col0 + bj * 128); u32x4 w;
;                     w.x = pg8::cvt_pk_bf16(v0[0] * silu_f(bflo(gz.x)), v0[1] * silu_f(bfhi(gz.x))); w.y = pg8::cvt_pk_bf16(v0[2] * silu_f(bflo(gz.y)), v0[3] * silu_f(bfhi(gz.y)));
;                     w.z = pg8::cvt_pk_bf16(v1[0] * silu_f(bflo(gz.z)), v1[1] * silu_f(bfhi(gz.z))); w.w = pg8::cvt_pk_bf16(v1[2] * silu_f(bflo(gz.w)), v1[3] * silu_f(bfhi(gz.w)));
;                     *(u32x4*)(O + row * DM + coff + col0 + bj * 128) = w; } }
	v_lshlrev_b32_e32 v78, 16, v74
	v_mul_f32_e32 v79, 0xbfb8aa3b, v78
	v_exp_f32_e32 v79, v79
	v_and_b32_e32 v74, 0xffff0000, v74
	v_add_f32_e32 v79, 1.0, v79
	v_div_scale_f32 v80, s[12:13], v79, v79, v78
	v_rcp_f32_e32 v81, v80
	s_nop 0
	v_fma_f32 v84, -v80, v81, 1.0
	v_fmac_f32_e32 v81, v84, v81
	v_div_scale_f32 v84, vcc, v78, v79, v78
	v_mul_f32_e32 v85, v84, v81
	v_fma_f32 v86, -v80, v85, v84
	v_fmac_f32_e32 v85, v86, v81
	v_fma_f32 v80, -v80, v85, v84
	v_div_fmas_f32 v80, v80, v81, v85
	v_div_fixup_f32 v78, v80, v79, v78
	v_mul_f32_e32 v70, v70, v78
	v_mul_f32_e32 v78, 0xbfb8aa3b, v74
	v_exp_f32_e32 v78, v78
	s_nop 0
	v_add_f32_e32 v78, 1.0, v78
	v_div_scale_f32 v79, s[12:13], v78, v78, v74
	v_rcp_f32_e32 v80, v79
	s_nop 0
	v_fma_f32 v81, -v79, v80, 1.0
	v_fmac_f32_e32 v80, v81, v80
	v_div_scale_f32 v81, vcc, v74, v78, v74
	v_mul_f32_e32 v84, v81, v80
	v_fma_f32 v85, -v79, v84, v81
	v_fmac_f32_e32 v84, v85, v80
	v_fma_f32 v79, -v79, v84, v81
	v_div_fmas_f32 v79, v79, v80, v84
	v_div_fixup_f32 v74, v79, v78, v74
	v_mul_f32_e32 v71, v71, v74
	v_cvt_pk_bf16_f32 v70, v70, v71
	v_lshlrev_b32_e32 v71, 16, v75
	v_mul_f32_e32 v74, 0xbfb8aa3b, v71
	v_exp_f32_e32 v74, v74
	s_nop 0
	v_add_f32_e32 v74, 1.0, v74
	v_div_scale_f32 v78, s[12:13], v74, v74, v71
	v_rcp_f32_e32 v79, v78
	s_nop 0
	v_fma_f32 v80, -v78, v79, 1.0
	v_fmac_f32_e32 v79, v80, v79
	v_div_scale_f32 v80, vcc, v71, v74, v71
	v_mul_f32_e32 v81, v80, v79
	v_fma_f32 v84, -v78, v81, v80
	v_fmac_f32_e32 v81, v84, v79
	v_fma_f32 v78, -v78, v81, v80
	v_div_fmas_f32 v78, v78, v79, v81
	v_div_fixup_f32 v71, v78, v74, v71
	v_mul_f32_e32 v71, v72, v71
	v_and_b32_e32 v72, 0xffff0000, v75
	v_mul_f32_e32 v74, 0xbfb8aa3b, v72
	v_exp_f32_e32 v74, v74
	s_nop 0
	v_add_f32_e32 v74, 1.0, v74
	v_div_scale_f32 v75, s[12:13], v74, v74, v72
	v_rcp_f32_e32 v78, v75
	s_nop 0
	v_fma_f32 v79, -v75, v78, 1.0
	v_fmac_f32_e32 v78, v79, v78
	v_div_scale_f32 v79, vcc, v72, v74, v72
	v_mul_f32_e32 v80, v79, v78
	v_fma_f32 v81, -v75, v80, v79
	v_fmac_f32_e32 v80, v81, v78
	v_fma_f32 v75, -v75, v80, v79
	v_div_fmas_f32 v75, v75, v78, v80
	v_div_fixup_f32 v72, v75, v74, v72
	v_mul_f32_e32 v72, v73, v72
	v_cvt_pk_bf16_f32 v71, v71, v72
	v_lshlrev_b32_e32 v72, 16, v76
	v_mul_f32_e32 v73, 0xbfb8aa3b, v72
	v_exp_f32_e32 v73, v73
	s_nop 0
	v_add_f32_e32 v73, 1.0, v73
	v_div_scale_f32 v74, s[12:13], v73, v73, v72
	v_rcp_f32_e32 v75, v74
	s_nop 0
	v_fma_f32 v78, -v74, v75, 1.0
	v_fmac_f32_e32 v75, v78, v75
	v_div_scale_f32 v78, vcc, v72, v73, v72
	v_mul_f32_e32 v79, v78, v75
	v_fma_f32 v80, -v74, v79, v78
	v_fmac_f32_e32 v79, v80, v75
	v_fma_f32 v74, -v74, v79, v78
	v_div_fmas_f32 v74, v74, v75, v79
	v_div_fixup_f32 v72, v74, v73, v72
	v_mul_f32_e32 v66, v66, v72
	v_and_b32_e32 v72, 0xffff0000, v76
	v_mul_f32_e32 v73, 0xbfb8aa3b, v72
	v_exp_f32_e32 v73, v73
	s_nop 0
	v_add_f32_e32 v73, 1.0, v73
	v_div_scale_f32 v74, s[12:13], v73, v73, v72
	v_rcp_f32_e32 v75, v74
	s_nop 0
	v_fma_f32 v76, -v74, v75, 1.0
	v_fmac_f32_e32 v75, v76, v75
	v_div_scale_f32 v76, vcc, v72, v73, v72
	v_mul_f32_e32 v78, v76, v75
	v_fma_f32 v79, -v74, v78, v76
	v_fmac_f32_e32 v78, v79, v75
	v_fma_f32 v74, -v74, v78, v76
	v_div_fmas_f32 v74, v74, v75, v78
	v_div_fixup_f32 v72, v74, v73, v72
	v_mul_f32_e32 v67, v67, v72
	v_cvt_pk_bf16_f32 v72, v66, v67
	v_lshlrev_b32_e32 v66, 16, v77
	v_mul_f32_e32 v67, 0xbfb8aa3b, v66
	v_exp_f32_e32 v67, v67
	s_nop 0
	v_add_f32_e32 v67, 1.0, v67
	v_div_scale_f32 v73, s[12:13], v67, v67, v66
	v_rcp_f32_e32 v74, v73
	s_nop 0
	v_fma_f32 v75, -v73, v74, 1.0
	v_fmac_f32_e32 v74, v75, v74
	v_div_scale_f32 v75, vcc, v66, v67, v66
	v_mul_f32_e32 v76, v75, v74
	v_fma_f32 v78, -v73, v76, v75
	v_fmac_f32_e32 v76, v78, v74
	v_fma_f32 v73, -v73, v76, v75
	v_div_fmas_f32 v73, v73, v74, v76
	v_div_fixup_f32 v66, v73, v67, v66
	v_and_b32_e32 v67, 0xffff0000, v77
	v_mul_f32_e32 v66, v68, v66
	v_mul_f32_e32 v68, 0xbfb8aa3b, v67
	v_exp_f32_e32 v68, v68
	s_nop 0
	v_add_f32_e32 v68, 1.0, v68
	v_div_scale_f32 v73, s[12:13], v68, v68, v67
	v_rcp_f32_e32 v74, v73
	s_nop 0
	v_fma_f32 v75, -v73, v74, 1.0
	v_fmac_f32_e32 v74, v75, v74
	v_div_scale_f32 v75, vcc, v67, v68, v67
	v_mul_f32_e32 v76, v75, v74
	v_fma_f32 v77, -v73, v76, v75
	v_fmac_f32_e32 v76, v77, v74
	v_fma_f32 v73, -v73, v76, v75
	v_div_fmas_f32 v73, v73, v74, v76
	v_div_fixup_f32 v67, v73, v68, v67
	v_mul_f32_e32 v67, v69, v67
	v_cvt_pk_bf16_f32 v73, v66, v67
	v_add_u32_e32 v66, 0x80, v160
	v_ashrrev_i32_e32 v67, 31, v66
	global_store_dwordx4 v[82:83], v[70:73], off offset:256
	s_nop 1
	v_lshlrev_b64 v[70:71], 12, v[66:67]
	v_mad_i64_i32 v[66:67], s[12:13], v66, s75, v[162:163]
	v_lshl_add_u64 v[66:67], v[66:67], 0, v[144:145]
	v_lshl_add_u64 v[72:73], v[66:67], 0, s[26:27]
	v_add_co_u32_e32 v66, vcc, s5, v66
	s_nop 1
	v_addc_co_u32_e32 v67, vcc, 0, v67, vcc
	global_load_dwordx4 v[66:69], v[66:67], off
	s_waitcnt vmcnt(0)
; __device__ __forceinline__ unsigned cvt_pk_bf16(float lo, float hi) { unsigned r; asm volatile("v_cvt_pk_bf16_f32 %0, %1, %2" : "=v"(r) : "v"(lo), "v"(hi)); return r; }
; __device__ __forceinline__ float bflo(unsigned u) { return __uint_as_float(u << 16); }
; __device__ __forceinline__ float bfhi(unsigned u) { return __uint_as_float(u & 0xffff0000u); }
; __device__ __forceinline__ float silu_f(float v) { return v / (1.f + __expf(-v)); }
;     __device__ __forceinline__ void operator()(const pg8::f32x4 (&acc)[2][2][4][2], const pg8::Unit& u, int wr, int wc, int fr, int fq) const {
;     ...
;             for (int m = 0; m < 4; ++m) { const size_t row = (size_t)(row0 + ai * 128 + m * 16);
; #pragma unroll
;                 for (int bj = 0; bj < 2; ++bj) { const pg8::f32x4 v0 = acc[ai][bj][m][0], v1 = acc[ai][bj][m][1];
;                     const u32x4 gz = *(const u32x4*)(Z + row * DIN + goff + col0 + bj * 128); u32x4 w;
;                     w.x = pg8::cvt_pk_bf16(v0[0] * silu_f(bflo(gz.x)), v0[1] * silu_f(bfhi(gz.x))); w.y = pg8::cvt_pk_bf16(v0[2] * silu_f(bflo(gz.y)), v0[3] * silu_f(bfhi(gz.y)));
;                     w.z = pg8::cvt_pk_bf16(v1[0] * silu_f(bflo(gz.z)), v1[1] * silu_f(bfhi(gz.z))); w.w = pg8::cvt_pk_bf16(v1[2] * silu_f(bflo(gz.w)), v1[3] * silu_f(bfhi(gz.w)));
;                     *(u32x4*)(O + row * DM + coff + col0 + bj * 128) = w; } }
	v_lshlrev_b32_e32 v74, 16, v66
	v_mul_f32_e32 v75, 0xbfb8aa3b, v74
	v_exp_f32_e32 v75, v75
	v_and_b32_e32 v66, 0xffff0000, v66
	v_add_f32_e32 v75, 1.0, v75
	v_div_scale_f32 v76, s[12:13], v75, v75, v74
	v_rcp_f32_e32 v77, v76
	s_nop 0
	v_fma_f32 v78, -v76, v77, 1.0
	v_fmac_f32_e32 v77, v78, v77
	v_div_scale_f32 v78, vcc, v74, v75, v74
	v_mul_f32_e32 v79, v78, v77
	v_fma_f32 v80, -v76, v79, v78
	v_fmac_f32_e32 v79, v80, v77
	v_fma_f32 v76, -v76, v79, v78
	v_div_fmas_f32 v76, v76, v77, v79
	v_div_fixup_f32 v74, v76, v75, v74
	v_mul_f32_e32 v62, v62, v74
	v_mul_f32_e32 v74, 0xbfb8aa3b, v66
	v_exp_f32_e32 v74, v74
	s_nop 0
	v_add_f32_e32 v74, 1.0, v74
	v_div_scale_f32 v75, s[12:13], v74, v74, v66
	v_rcp_f32_e32 v76, v75
	s_nop 0
	v_fma_f32 v77, -v75, v76, 1.0
	v_fmac_f32_e32 v76, v77, v76
	v_div_scale_f32 v77, vcc, v66, v74, v66
	v_mul_f32_e32 v78, v77, v76
	v_fma_f32 v79, -v75, v78, v77
	v_fmac_f32_e32 v78, v79, v76
	v_fma_f32 v75, -v75, v78, v77
	v_div_fmas_f32 v75, v75, v76, v78
	v_div_fixup_f32 v66, v75, v74, v66
	v_mul_f32_e32 v63, v63, v66
	v_cvt_pk_bf16_f32 v62, v62, v63
	v_lshlrev_b32_e32 v63, 16, v67
	v_mul_f32_e32 v66, 0xbfb8aa3b, v63
	v_exp_f32_e32 v66, v66
	s_nop 0
	v_add_f32_e32 v66, 1.0, v66
	v_div_scale_f32 v74, s[12:13], v66, v66, v63
	v_rcp_f32_e32 v75, v74
	s_nop 0
	v_fma_f32 v76, -v74, v75, 1.0
	v_fmac_f32_e32 v75, v76, v75
	v_div_scale_f32 v76, vcc, v63, v66, v63
	v_mul_f32_e32 v77, v76, v75
	v_fma_f32 v78, -v74, v77, v76
	v_fmac_f32_e32 v77, v78, v75
	v_fma_f32 v74, -v74, v77, v76
	v_div_fmas_f32 v74, v74, v75, v77
	v_div_fixup_f32 v63, v74, v66, v63
	v_mul_f32_e32 v63, v64, v63
	v_and_b32_e32 v64, 0xffff0000, v67
	v_mul_f32_e32 v66, 0xbfb8aa3b, v64
	v_exp_f32_e32 v66, v66
	s_nop 0
	v_add_f32_e32 v66, 1.0, v66
	v_div_scale_f32 v67, s[12:13], v66, v66, v64
	v_rcp_f32_e32 v74, v67
	s_nop 0
	v_fma_f32 v75, -v67, v74, 1.0
	v_fmac_f32_e32 v74, v75, v74
	v_div_scale_f32 v75, vcc, v64, v66, v64
	v_mul_f32_e32 v76, v75, v74
	v_fma_f32 v77, -v67, v76, v75
	v_fmac_f32_e32 v76, v77, v74
	v_fma_f32 v67, -v67, v76, v75
	v_div_fmas_f32 v67, v67, v74, v76
	v_div_fixup_f32 v64, v67, v66, v64
	v_mul_f32_e32 v64, v65, v64
	v_cvt_pk_bf16_f32 v63, v63, v64
	v_lshlrev_b32_e32 v64, 16, v68
	v_mul_f32_e32 v65, 0xbfb8aa3b, v64
	v_exp_f32_e32 v65, v65
	s_nop 0
	v_add_f32_e32 v65, 1.0, v65
	v_div_scale_f32 v66, s[12:13], v65, v65, v64
	v_rcp_f32_e32 v67, v66
	s_nop 0
	v_fma_f32 v74, -v66, v67, 1.0
	v_fmac_f32_e32 v67, v74, v67
	v_div_scale_f32 v74, vcc, v64, v65, v64
	v_mul_f32_e32 v75, v74, v67
	v_fma_f32 v76, -v66, v75, v74
	v_fmac_f32_e32 v75, v76, v67
	v_fma_f32 v66, -v66, v75, v74
	v_div_fmas_f32 v66, v66, v67, v75
	v_div_fixup_f32 v64, v66, v65, v64
	v_mul_f32_e32 v58, v58, v64
	v_and_b32_e32 v64, 0xffff0000, v68
	v_mul_f32_e32 v65, 0xbfb8aa3b, v64
	v_exp_f32_e32 v65, v65
	s_nop 0
	v_add_f32_e32 v65, 1.0, v65
	v_div_scale_f32 v66, s[12:13], v65, v65, v64
	v_rcp_f32_e32 v67, v66
	s_nop 0
	v_fma_f32 v68, -v66, v67, 1.0
	v_fmac_f32_e32 v67, v68, v67
	v_div_scale_f32 v68, vcc, v64, v65, v64
	v_mul_f32_e32 v74, v68, v67
	v_fma_f32 v75, -v66, v74, v68
	v_fmac_f32_e32 v74, v75, v67
	v_fma_f32 v66, -v66, v74, v68
	v_div_fmas_f32 v66, v66, v67, v74
	v_div_fixup_f32 v64, v66, v65, v64
	v_mul_f32_e32 v59, v59, v64
	v_cvt_pk_bf16_f32 v64, v58, v59
	v_lshlrev_b32_e32 v58, 16, v69
	v_mul_f32_e32 v59, 0xbfb8aa3b, v58
	v_exp_f32_e32 v59, v59
	s_nop 0
	v_add_f32_e32 v59, 1.0, v59
	v_div_scale_f32 v65, s[12:13], v59, v59, v58
	v_rcp_f32_e32 v66, v65
	s_nop 0
	v_fma_f32 v67, -v65, v66, 1.0
	v_fmac_f32_e32 v66, v67, v66
	v_div_scale_f32 v67, vcc, v58, v59, v58
	v_mul_f32_e32 v68, v67, v66
	v_fma_f32 v74, -v65, v68, v67
	v_fmac_f32_e32 v68, v74, v66
	v_fma_f32 v65, -v65, v68, v67
	v_div_fmas_f32 v65, v65, v66, v68
	v_div_fixup_f32 v58, v65, v59, v58
	v_and_b32_e32 v59, 0xffff0000, v69
	v_mul_f32_e32 v58, v60, v58
	v_mul_f32_e32 v60, 0xbfb8aa3b, v59
	v_exp_f32_e32 v60, v60
	s_nop 0
	v_add_f32_e32 v60, 1.0, v60
	v_div_scale_f32 v65, s[12:13], v60, v60, v59
	v_rcp_f32_e32 v66, v65
	s_nop 0
	v_fma_f32 v67, -v65, v66, 1.0
	v_fmac_f32_e32 v66, v67, v66
	v_div_scale_f32 v67, vcc, v59, v60, v59
	v_mul_f32_e32 v68, v67, v66
	v_fma_f32 v69, -v65, v68, v67
	v_fmac_f32_e32 v68, v69, v66
	v_fma_f32 v65, -v65, v68, v67
	v_div_fmas_f32 v65, v65, v66, v68
	v_div_fixup_f32 v59, v65, v60, v59
	v_mul_f32_e32 v59, v61, v59
	v_cvt_pk_bf16_f32 v65, v58, v59
	v_lshl_add_u64 v[58:59], s[72:73], 0, v[70:71]
	v_lshl_add_u64 v[66:67], v[58:59], 0, v[144:145]
	global_store_dwordx4 v[66:67], v[62:65], off
	global_load_dwordx4 v[58:61], v[72:73], off offset:256
	s_waitcnt vmcnt(0)
; __device__ __forceinline__ unsigned cvt_pk_bf16(float lo, float hi) { unsigned r; asm volatile("v_cvt_pk_bf16_f32 %0, %1, %2" : "=v"(r) : "v"(lo), "v"(hi)); return r; }
; __device__ __forceinline__ float bflo(unsigned u) { return __uint_as_float(u << 16); }
; __device__ __forceinline__ float bfhi(unsigned u) { return __uint_as_float(u & 0xffff0000u); }
; __device__ __forceinline__ float silu_f(float v) { return v / (1.f + __expf(-v)); }
;     __device__ __forceinline__ void operator()(const pg8::f32x4 (&acc)[2][2][4][2], const pg8::Unit& u, int wr, int wc, int fr, int fq) const {
;     ...
;             for (int m = 0; m < 4; ++m) { const size_t row = (size_t)(row0 + ai * 128 + m * 16);
; #pragma unroll
;                 for (int bj = 0; bj < 2; ++bj) { const pg8::f32x4 v0 = acc[ai][bj][m][0], v1 = acc[ai][bj][m][1];
;                     const u32x4 gz = *(const u32x4*)(Z + row * DIN + goff + col0 + bj * 128); u32x4 w;
;                     w.x = pg8::cvt_pk_bf16(v0[0] * silu_f(bflo(gz.x)), v0[1] * silu_f(bfhi(gz.x))); w.y = pg8::cvt_pk_bf16(v0[2] * silu_f(bflo(gz.y)), v0[3] * silu_f(bfhi(gz.y)));
;                     w.z = pg8::cvt_pk_bf16(v1[0] * silu_f(bflo(gz.z)), v1[1] * silu_f(bfhi(gz.z))); w.w = pg8::cvt_pk_bf16(v1[2] * silu_f(bflo(gz.w)), v1[3] * silu_f(bfhi(gz.w)));
;                     *(u32x4*)(O + row * DM + coff + col0 + bj * 128) = w; } }
	v_lshlrev_b32_e32 v62, 16, v58
	v_mul_f32_e32 v63, 0xbfb8aa3b, v62
	v_exp_f32_e32 v63, v63
	v_and_b32_e32 v58, 0xffff0000, v58
	v_add_f32_e32 v63, 1.0, v63
	v_div_scale_f32 v64, s[12:13], v63, v63, v62
	v_rcp_f32_e32 v65, v64
	s_nop 0
	v_fma_f32 v68, -v64, v65, 1.0
	v_fmac_f32_e32 v65, v68, v65
	v_div_scale_f32 v68, vcc, v62, v63, v62
	v_mul_f32_e32 v69, v68, v65
	v_fma_f32 v70, -v64, v69, v68
	v_fmac_f32_e32 v69, v70, v65
	v_fma_f32 v64, -v64, v69, v68
	v_div_fmas_f32 v64, v64, v65, v69
	v_div_fixup_f32 v62, v64, v63, v62
	v_mul_f32_e32 v54, v54, v62
	v_mul_f32_e32 v62, 0xbfb8aa3b, v58
	v_exp_f32_e32 v62, v62
	s_nop 0
	v_add_f32_e32 v62, 1.0, v62
	v_div_scale_f32 v63, s[12:13], v62, v62, v58
	v_rcp_f32_e32 v64, v63
	s_nop 0
	v_fma_f32 v65, -v63, v64, 1.0
	v_fmac_f32_e32 v64, v65, v64
	v_div_scale_f32 v65, vcc, v58, v62, v58
	v_mul_f32_e32 v68, v65, v64
	v_fma_f32 v69, -v63, v68, v65
	v_fmac_f32_e32 v68, v69, v64
	v_fma_f32 v63, -v63, v68, v65
	v_div_fmas_f32 v63, v63, v64, v68
	v_div_fixup_f32 v58, v63, v62, v58
	v_mul_f32_e32 v55, v55, v58
	v_cvt_pk_bf16_f32 v54, v54, v55
	v_lshlrev_b32_e32 v55, 16, v59
	v_mul_f32_e32 v58, 0xbfb8aa3b, v55
	v_exp_f32_e32 v58, v58
	s_nop 0
	v_add_f32_e32 v58, 1.0, v58
	v_div_scale_f32 v62, s[12:13], v58, v58, v55
	v_rcp_f32_e32 v63, v62
	s_nop 0
	v_fma_f32 v64, -v62, v63, 1.0
	v_fmac_f32_e32 v63, v64, v63
	v_div_scale_f32 v64, vcc, v55, v58, v55
	v_mul_f32_e32 v65, v64, v63
	v_fma_f32 v68, -v62, v65, v64
	v_fmac_f32_e32 v65, v68, v63
	v_fma_f32 v62, -v62, v65, v64
	v_div_fmas_f32 v62, v62, v63, v65
	v_div_fixup_f32 v55, v62, v58, v55
	v_mul_f32_e32 v55, v56, v55
	v_and_b32_e32 v56, 0xffff0000, v59
	v_mul_f32_e32 v58, 0xbfb8aa3b, v56
	v_exp_f32_e32 v58, v58
	s_nop 0
	v_add_f32_e32 v58, 1.0, v58
	v_div_scale_f32 v59, s[12:13], v58, v58, v56
	v_rcp_f32_e32 v62, v59
	s_nop 0
	v_fma_f32 v63, -v59, v62, 1.0
	v_fmac_f32_e32 v62, v63, v62
	v_div_scale_f32 v63, vcc, v56, v58, v56
	v_mul_f32_e32 v64, v63, v62
	v_fma_f32 v65, -v59, v64, v63
	v_fmac_f32_e32 v64, v65, v62
	v_fma_f32 v59, -v59, v64, v63
	v_div_fmas_f32 v59, v59, v62, v64
	v_div_fixup_f32 v56, v59, v58, v56
	v_mul_f32_e32 v56, v57, v56
	v_cvt_pk_bf16_f32 v55, v55, v56
	v_lshlrev_b32_e32 v56, 16, v60
	v_mul_f32_e32 v57, 0xbfb8aa3b, v56
	v_exp_f32_e32 v57, v57
	s_nop 0
	v_add_f32_e32 v57, 1.0, v57
	v_div_scale_f32 v58, s[12:13], v57, v57, v56
	v_rcp_f32_e32 v59, v58
	s_nop 0
	v_fma_f32 v62, -v58, v59, 1.0
	v_fmac_f32_e32 v59, v62, v59
	v_div_scale_f32 v62, vcc, v56, v57, v56
	v_mul_f32_e32 v63, v62, v59
	v_fma_f32 v64, -v58, v63, v62
	v_fmac_f32_e32 v63, v64, v59
	v_fma_f32 v58, -v58, v63, v62
	v_div_fmas_f32 v58, v58, v59, v63
	v_div_fixup_f32 v56, v58, v57, v56
	v_mul_f32_e32 v50, v50, v56
	v_and_b32_e32 v56, 0xffff0000, v60
	v_mul_f32_e32 v57, 0xbfb8aa3b, v56
	v_exp_f32_e32 v57, v57
	s_nop 0
	v_add_f32_e32 v57, 1.0, v57
	v_div_scale_f32 v58, s[12:13], v57, v57, v56
	v_rcp_f32_e32 v59, v58
	s_nop 0
	v_fma_f32 v60, -v58, v59, 1.0
	v_fmac_f32_e32 v59, v60, v59
	v_div_scale_f32 v60, vcc, v56, v57, v56
	v_mul_f32_e32 v62, v60, v59
	v_fma_f32 v63, -v58, v62, v60
	v_fmac_f32_e32 v62, v63, v59
	v_fma_f32 v58, -v58, v62, v60
	v_div_fmas_f32 v58, v58, v59, v62
	v_div_fixup_f32 v56, v58, v57, v56
	v_mul_f32_e32 v51, v51, v56
	v_cvt_pk_bf16_f32 v56, v50, v51
	v_lshlrev_b32_e32 v50, 16, v61
	v_mul_f32_e32 v51, 0xbfb8aa3b, v50
	v_exp_f32_e32 v51, v51
	s_nop 0
	v_add_f32_e32 v51, 1.0, v51
	v_div_scale_f32 v57, s[12:13], v51, v51, v50
	v_rcp_f32_e32 v58, v57
	s_nop 0
	v_fma_f32 v59, -v57, v58, 1.0
	v_fmac_f32_e32 v58, v59, v58
	v_div_scale_f32 v59, vcc, v50, v51, v50
	v_mul_f32_e32 v60, v59, v58
	v_fma_f32 v62, -v57, v60, v59
	v_fmac_f32_e32 v60, v62, v58
	v_fma_f32 v57, -v57, v60, v59
	v_div_fmas_f32 v57, v57, v58, v60
	v_div_fixup_f32 v50, v57, v51, v50
	v_and_b32_e32 v51, 0xffff0000, v61
	v_mul_f32_e32 v50, v52, v50
	v_mul_f32_e32 v52, 0xbfb8aa3b, v51
	v_exp_f32_e32 v52, v52
	s_nop 0
	v_add_f32_e32 v52, 1.0, v52
	v_div_scale_f32 v57, s[12:13], v52, v52, v51
	v_rcp_f32_e32 v58, v57
	s_nop 0
	v_fma_f32 v59, -v57, v58, 1.0
	v_fmac_f32_e32 v58, v59, v58
	v_div_scale_f32 v59, vcc, v51, v52, v51
	v_mul_f32_e32 v60, v59, v58
	v_fma_f32 v61, -v57, v60, v59
	v_fmac_f32_e32 v60, v61, v58
	v_fma_f32 v57, -v57, v60, v59
	v_div_fmas_f32 v57, v57, v58, v60
	v_div_fixup_f32 v51, v57, v52, v51
	v_mul_f32_e32 v51, v53, v51
	v_cvt_pk_bf16_f32 v57, v50, v51
	v_add_u32_e32 v50, 0x90, v160
	v_ashrrev_i32_e32 v51, 31, v50
	global_store_dwordx4 v[66:67], v[54:57], off offset:256
	s_nop 1
	v_lshlrev_b64 v[54:55], 12, v[50:51]
	v_mad_i64_i32 v[50:51], s[12:13], v50, s75, v[162:163]
	v_lshl_add_u64 v[50:51], v[50:51], 0, v[144:145]
	v_lshl_add_u64 v[56:57], v[50:51], 0, s[26:27]
	v_add_co_u32_e32 v50, vcc, s5, v50
	s_nop 1
	v_addc_co_u32_e32 v51, vcc, 0, v51, vcc
	global_load_dwordx4 v[50:53], v[50:51], off
	s_waitcnt vmcnt(0)
; __device__ __forceinline__ unsigned cvt_pk_bf16(float lo, float hi) { unsigned r; asm volatile("v_cvt_pk_bf16_f32 %0, %1, %2" : "=v"(r) : "v"(lo), "v"(hi)); return r; }
; __device__ __forceinline__ float bflo(unsigned u) { return __uint_as_float(u << 16); }
; __device__ __forceinline__ float bfhi(unsigned u) { return __uint_as_float(u & 0xffff0000u); }
; __device__ __forceinline__ float silu_f(float v) { return v / (1.f + __expf(-v)); }
;     __device__ __forceinline__ void operator()(const pg8::f32x4 (&acc)[2][2][4][2], const pg8::Unit& u, int wr, int wc, int fr, int fq) const {
;     ...
;             for (int m = 0; m < 4; ++m) { const size_t row = (size_t)(row0 + ai * 128 + m * 16);
; #pragma unroll
;                 for (int bj = 0; bj < 2; ++bj) { const pg8::f32x4 v0 = acc[ai][bj][m][0], v1 = acc[ai][bj][m][1];
;                     const u32x4 gz = *(const u32x4*)(Z + row * DIN + goff + col0 + bj * 128); u32x4 w;
;                     w.x = pg8::cvt_pk_bf16(v0[0] * silu_f(bflo(gz.x)), v0[1] * silu_f(bfhi(gz.x))); w.y = pg8::cvt_pk_bf16(v0[2] * silu_f(bflo(gz.y)), v0[3] * silu_f(bfhi(gz.y)));
;                     w.z = pg8::cvt_pk_bf16(v1[0] * silu_f(bflo(gz.z)), v1[1] * silu_f(bfhi(gz.z))); w.w = pg8::cvt_pk_bf16(v1[2] * silu_f(bflo(gz.w)), v1[3] * silu_f(bfhi(gz.w)));
;                     *(u32x4*)(O + row * DM + coff + col0 + bj * 128) = w; } }
	v_lshlrev_b32_e32 v58, 16, v50
	v_mul_f32_e32 v59, 0xbfb8aa3b, v58
	v_exp_f32_e32 v59, v59
	v_and_b32_e32 v50, 0xffff0000, v50
	v_add_f32_e32 v59, 1.0, v59
	v_div_scale_f32 v60, s[12:13], v59, v59, v58
	v_rcp_f32_e32 v61, v60
	s_nop 0
	v_fma_f32 v62, -v60, v61, 1.0
	v_fmac_f32_e32 v61, v62, v61
	v_div_scale_f32 v62, vcc, v58, v59, v58
	v_mul_f32_e32 v63, v62, v61
	v_fma_f32 v64, -v60, v63, v62
	v_fmac_f32_e32 v63, v64, v61
	v_fma_f32 v60, -v60, v63, v62
	v_div_fmas_f32 v60, v60, v61, v63
	v_div_fixup_f32 v58, v60, v59, v58
	v_mul_f32_e32 v46, v46, v58
	v_mul_f32_e32 v58, 0xbfb8aa3b, v50
	v_exp_f32_e32 v58, v58
	s_nop 0
	v_add_f32_e32 v58, 1.0, v58
	v_div_scale_f32 v59, s[12:13], v58, v58, v50
	v_rcp_f32_e32 v60, v59
	s_nop 0
	v_fma_f32 v61, -v59, v60, 1.0
	v_fmac_f32_e32 v60, v61, v60
	v_div_scale_f32 v61, vcc, v50, v58, v50
	v_mul_f32_e32 v62, v61, v60
	v_fma_f32 v63, -v59, v62, v61
	v_fmac_f32_e32 v62, v63, v60
	v_fma_f32 v59, -v59, v62, v61
	v_div_fmas_f32 v59, v59, v60, v62
	v_div_fixup_f32 v50, v59, v58, v50
	v_mul_f32_e32 v47, v47, v50
	v_cvt_pk_bf16_f32 v46, v46, v47
	v_lshlrev_b32_e32 v47, 16, v51
	v_mul_f32_e32 v50, 0xbfb8aa3b, v47
	v_exp_f32_e32 v50, v50
	s_nop 0
	v_add_f32_e32 v50, 1.0, v50
	v_div_scale_f32 v58, s[12:13], v50, v50, v47
	v_rcp_f32_e32 v59, v58
	s_nop 0
	v_fma_f32 v60, -v58, v59, 1.0
	v_fmac_f32_e32 v59, v60, v59
	v_div_scale_f32 v60, vcc, v47, v50, v47
	v_mul_f32_e32 v61, v60, v59
	v_fma_f32 v62, -v58, v61, v60
	v_fmac_f32_e32 v61, v62, v59
	v_fma_f32 v58, -v58, v61, v60
	v_div_fmas_f32 v58, v58, v59, v61
	v_div_fixup_f32 v47, v58, v50, v47
	v_mul_f32_e32 v47, v48, v47
	v_and_b32_e32 v48, 0xffff0000, v51
	v_mul_f32_e32 v50, 0xbfb8aa3b, v48
	v_exp_f32_e32 v50, v50
	s_nop 0
	v_add_f32_e32 v50, 1.0, v50
	v_div_scale_f32 v51, s[12:13], v50, v50, v48
	v_rcp_f32_e32 v58, v51
	s_nop 0
	v_fma_f32 v59, -v51, v58, 1.0
	v_fmac_f32_e32 v58, v59, v58
	v_div_scale_f32 v59, vcc, v48, v50, v48
	v_mul_f32_e32 v60, v59, v58
	v_fma_f32 v61, -v51, v60, v59
	v_fmac_f32_e32 v60, v61, v58
	v_fma_f32 v51, -v51, v60, v59
	v_div_fmas_f32 v51, v51, v58, v60
	v_div_fixup_f32 v48, v51, v50, v48
	v_mul_f32_e32 v48, v49, v48
	v_cvt_pk_bf16_f32 v47, v47, v48
	v_lshlrev_b32_e32 v48, 16, v52
	v_mul_f32_e32 v49, 0xbfb8aa3b, v48
	v_exp_f32_e32 v49, v49
	s_nop 0
	v_add_f32_e32 v49, 1.0, v49
	v_div_scale_f32 v50, s[12:13], v49, v49, v48
	v_rcp_f32_e32 v51, v50
	s_nop 0
	v_fma_f32 v58, -v50, v51, 1.0
	v_fmac_f32_e32 v51, v58, v51
	v_div_scale_f32 v58, vcc, v48, v49, v48
	v_mul_f32_e32 v59, v58, v51
	v_fma_f32 v60, -v50, v59, v58
	v_fmac_f32_e32 v59, v60, v51
	v_fma_f32 v50, -v50, v59, v58
	v_div_fmas_f32 v50, v50, v51, v59
	v_div_fixup_f32 v48, v50, v49, v48
	v_mul_f32_e32 v42, v42, v48
	v_and_b32_e32 v48, 0xffff0000, v52
	v_mul_f32_e32 v49, 0xbfb8aa3b, v48
	v_exp_f32_e32 v49, v49
	s_nop 0
	v_add_f32_e32 v49, 1.0, v49
	v_div_scale_f32 v50, s[12:13], v49, v49, v48
	v_rcp_f32_e32 v51, v50
	s_nop 0
	v_fma_f32 v52, -v50, v51, 1.0
	v_fmac_f32_e32 v51, v52, v51
	v_div_scale_f32 v52, vcc, v48, v49, v48
	v_mul_f32_e32 v58, v52, v51
	v_fma_f32 v59, -v50, v58, v52
	v_fmac_f32_e32 v58, v59, v51
	v_fma_f32 v50, -v50, v58, v52
	v_div_fmas_f32 v50, v50, v51, v58
	v_div_fixup_f32 v48, v50, v49, v48
	v_mul_f32_e32 v43, v43, v48
	v_cvt_pk_bf16_f32 v48, v42, v43
	v_lshlrev_b32_e32 v42, 16, v53
	v_mul_f32_e32 v43, 0xbfb8aa3b, v42
	v_exp_f32_e32 v43, v43
	s_nop 0
	v_add_f32_e32 v43, 1.0, v43
	v_div_scale_f32 v49, s[12:13], v43, v43, v42
	v_rcp_f32_e32 v50, v49
	s_nop 0
	v_fma_f32 v51, -v49, v50, 1.0
	v_fmac_f32_e32 v50, v51, v50
	v_div_scale_f32 v51, vcc, v42, v43, v42
	v_mul_f32_e32 v52, v51, v50
	v_fma_f32 v58, -v49, v52, v51
	v_fmac_f32_e32 v52, v58, v50
	v_fma_f32 v49, -v49, v52, v51
	v_div_fmas_f32 v49, v49, v50, v52
	v_div_fixup_f32 v42, v49, v43, v42
	v_and_b32_e32 v43, 0xffff0000, v53
	v_mul_f32_e32 v42, v44, v42
	v_mul_f32_e32 v44, 0xbfb8aa3b, v43
	v_exp_f32_e32 v44, v44
	s_nop 0
	v_add_f32_e32 v44, 1.0, v44
	v_div_scale_f32 v49, s[12:13], v44, v44, v43
	v_rcp_f32_e32 v50, v49
	s_nop 0
	v_fma_f32 v51, -v49, v50, 1.0
	v_fmac_f32_e32 v50, v51, v50
	v_div_scale_f32 v51, vcc, v43, v44, v43
	v_mul_f32_e32 v52, v51, v50
	v_fma_f32 v53, -v49, v52, v51
	v_fmac_f32_e32 v52, v53, v50
	v_fma_f32 v49, -v49, v52, v51
	v_div_fmas_f32 v49, v49, v50, v52
	v_div_fixup_f32 v43, v49, v44, v43
	v_mul_f32_e32 v43, v45, v43
	v_cvt_pk_bf16_f32 v49, v42, v43
	v_lshl_add_u64 v[42:43], s[72:73], 0, v[54:55]
	v_lshl_add_u64 v[50:51], v[42:43], 0, v[144:145]
	global_store_dwordx4 v[50:51], v[46:49], off
	global_load_dwordx4 v[42:45], v[56:57], off offset:256
	s_waitcnt vmcnt(0)
; __device__ __forceinline__ unsigned cvt_pk_bf16(float lo, float hi) { unsigned r; asm volatile("v_cvt_pk_bf16_f32 %0, %1, %2" : "=v"(r) : "v"(lo), "v"(hi)); return r; }
; __device__ __forceinline__ float bflo(unsigned u) { return __uint_as_float(u << 16); }
; __device__ __forceinline__ float bfhi(unsigned u) { return __uint_as_float(u & 0xffff0000u); }
; __device__ __forceinline__ float silu_f(float v) { return v / (1.f + __expf(-v)); }
;     __device__ __forceinline__ void operator()(const pg8::f32x4 (&acc)[2][2][4][2], const pg8::Unit& u, int wr, int wc, int fr, int fq) const {
;     ...
;             for (int m = 0; m < 4; ++m) { const size_t row = (size_t)(row0 + ai * 128 + m * 16);
; #pragma unroll
;                 for (int bj = 0; bj < 2; ++bj) { const pg8::f32x4 v0 = acc[ai][bj][m][0], v1 = acc[ai][bj][m][1];
;                     const u32x4 gz = *(const u32x4*)(Z + row * DIN + goff + col0 + bj * 128); u32x4 w;
;                     w.x = pg8::cvt_pk_bf16(v0[0] * silu_f(bflo(gz.x)), v0[1] * silu_f(bfhi(gz.x))); w.y = pg8::cvt_pk_bf16(v0[2] * silu_f(bflo(gz.y)), v0[3] * silu_f(bfhi(gz.y)));
;                     w.z = pg8::cvt_pk_bf16(v1[0] * silu_f(bflo(gz.z)), v1[1] * silu_f(bfhi(gz.z))); w.w = pg8::cvt_pk_bf16(v1[2] * silu_f(bflo(gz.w)), v1[3] * silu_f(bfhi(gz.w)));
;                     *(u32x4*)(O + row * DM + coff + col0 + bj * 128) = w; } }
	v_lshlrev_b32_e32 v46, 16, v42
	v_mul_f32_e32 v47, 0xbfb8aa3b, v46
	v_exp_f32_e32 v47, v47
	v_and_b32_e32 v42, 0xffff0000, v42
	v_add_f32_e32 v47, 1.0, v47
	v_div_scale_f32 v48, s[12:13], v47, v47, v46
	v_rcp_f32_e32 v49, v48
	s_nop 0
	v_fma_f32 v52, -v48, v49, 1.0
	v_fmac_f32_e32 v49, v52, v49
	v_div_scale_f32 v52, vcc, v46, v47, v46
	v_mul_f32_e32 v53, v52, v49
	v_fma_f32 v54, -v48, v53, v52
	v_fmac_f32_e32 v53, v54, v49
	v_fma_f32 v48, -v48, v53, v52
	v_div_fmas_f32 v48, v48, v49, v53
	v_div_fixup_f32 v46, v48, v47, v46
	v_mul_f32_e32 v38, v38, v46
	v_mul_f32_e32 v46, 0xbfb8aa3b, v42
	v_exp_f32_e32 v46, v46
	s_nop 0
	v_add_f32_e32 v46, 1.0, v46
	v_div_scale_f32 v47, s[12:13], v46, v46, v42
	v_rcp_f32_e32 v48, v47
	s_nop 0
	v_fma_f32 v49, -v47, v48, 1.0
	v_fmac_f32_e32 v48, v49, v48
	v_div_scale_f32 v49, vcc, v42, v46, v42
	v_mul_f32_e32 v52, v49, v48
	v_fma_f32 v53, -v47, v52, v49
	v_fmac_f32_e32 v52, v53, v48
	v_fma_f32 v47, -v47, v52, v49
	v_div_fmas_f32 v47, v47, v48, v52
	v_div_fixup_f32 v42, v47, v46, v42
	v_mul_f32_e32 v39, v39, v42
	v_cvt_pk_bf16_f32 v38, v38, v39
	v_lshlrev_b32_e32 v39, 16, v43
	v_mul_f32_e32 v42, 0xbfb8aa3b, v39
	v_exp_f32_e32 v42, v42
	s_nop 0
	v_add_f32_e32 v42, 1.0, v42
	v_div_scale_f32 v46, s[12:13], v42, v42, v39
	v_rcp_f32_e32 v47, v46
	s_nop 0
	v_fma_f32 v48, -v46, v47, 1.0
	v_fmac_f32_e32 v47, v48, v47
	v_div_scale_f32 v48, vcc, v39, v42, v39
	v_mul_f32_e32 v49, v48, v47
	v_fma_f32 v52, -v46, v49, v48
	v_fmac_f32_e32 v49, v52, v47
	v_fma_f32 v46, -v46, v49, v48
	v_div_fmas_f32 v46, v46, v47, v49
	v_div_fixup_f32 v39, v46, v42, v39
	v_mul_f32_e32 v39, v40, v39
	v_and_b32_e32 v40, 0xffff0000, v43
	v_mul_f32_e32 v42, 0xbfb8aa3b, v40
	v_exp_f32_e32 v42, v42
	s_nop 0
	v_add_f32_e32 v42, 1.0, v42
	v_div_scale_f32 v43, s[12:13], v42, v42, v40
	v_rcp_f32_e32 v46, v43
	s_nop 0
	v_fma_f32 v47, -v43, v46, 1.0
	v_fmac_f32_e32 v46, v47, v46
	v_div_scale_f32 v47, vcc, v40, v42, v40
	v_mul_f32_e32 v48, v47, v46
	v_fma_f32 v49, -v43, v48, v47
	v_fmac_f32_e32 v48, v49, v46
	v_fma_f32 v43, -v43, v48, v47
	v_div_fmas_f32 v43, v43, v46, v48
	v_div_fixup_f32 v40, v43, v42, v40
	v_mul_f32_e32 v40, v41, v40
	v_cvt_pk_bf16_f32 v39, v39, v40
	v_lshlrev_b32_e32 v40, 16, v44
	v_mul_f32_e32 v41, 0xbfb8aa3b, v40
	v_exp_f32_e32 v41, v41
	s_nop 0
	v_add_f32_e32 v41, 1.0, v41
	v_div_scale_f32 v42, s[12:13], v41, v41, v40
	v_rcp_f32_e32 v43, v42
	s_nop 0
	v_fma_f32 v46, -v42, v43, 1.0
	v_fmac_f32_e32 v43, v46, v43
	v_div_scale_f32 v46, vcc, v40, v41, v40
	v_mul_f32_e32 v47, v46, v43
	v_fma_f32 v48, -v42, v47, v46
	v_fmac_f32_e32 v47, v48, v43
	v_fma_f32 v42, -v42, v47, v46
	v_div_fmas_f32 v42, v42, v43, v47
	v_div_fixup_f32 v40, v42, v41, v40
	v_mul_f32_e32 v34, v34, v40
	v_and_b32_e32 v40, 0xffff0000, v44
	v_mul_f32_e32 v41, 0xbfb8aa3b, v40
	v_exp_f32_e32 v41, v41
	s_nop 0
	v_add_f32_e32 v41, 1.0, v41
	v_div_scale_f32 v42, s[12:13], v41, v41, v40
	v_rcp_f32_e32 v43, v42
	s_nop 0
	v_fma_f32 v44, -v42, v43, 1.0
	v_fmac_f32_e32 v43, v44, v43
	v_div_scale_f32 v44, vcc, v40, v41, v40
	v_mul_f32_e32 v46, v44, v43
	v_fma_f32 v47, -v42, v46, v44
	v_fmac_f32_e32 v46, v47, v43
	v_fma_f32 v42, -v42, v46, v44
	v_div_fmas_f32 v42, v42, v43, v46
	v_div_fixup_f32 v40, v42, v41, v40
	v_mul_f32_e32 v35, v35, v40
	v_cvt_pk_bf16_f32 v40, v34, v35
	v_lshlrev_b32_e32 v34, 16, v45
	v_mul_f32_e32 v35, 0xbfb8aa3b, v34
	v_exp_f32_e32 v35, v35
	s_nop 0
	v_add_f32_e32 v35, 1.0, v35
	v_div_scale_f32 v41, s[12:13], v35, v35, v34
	v_rcp_f32_e32 v42, v41
	s_nop 0
	v_fma_f32 v43, -v41, v42, 1.0
	v_fmac_f32_e32 v42, v43, v42
	v_div_scale_f32 v43, vcc, v34, v35, v34
	v_mul_f32_e32 v44, v43, v42
	v_fma_f32 v46, -v41, v44, v43
	v_fmac_f32_e32 v44, v46, v42
	v_fma_f32 v41, -v41, v44, v43
	v_div_fmas_f32 v41, v41, v42, v44
	v_div_fixup_f32 v34, v41, v35, v34
	v_and_b32_e32 v35, 0xffff0000, v45
	v_mul_f32_e32 v34, v36, v34
	v_mul_f32_e32 v36, 0xbfb8aa3b, v35
	v_exp_f32_e32 v36, v36
	s_nop 0
	v_add_f32_e32 v36, 1.0, v36
	v_div_scale_f32 v41, s[12:13], v36, v36, v35
	v_rcp_f32_e32 v42, v41
	s_nop 0
	v_fma_f32 v43, -v41, v42, 1.0
	v_fmac_f32_e32 v42, v43, v42
	v_div_scale_f32 v43, vcc, v35, v36, v35
	v_mul_f32_e32 v44, v43, v42
	v_fma_f32 v45, -v41, v44, v43
	v_fmac_f32_e32 v44, v45, v42
	v_fma_f32 v41, -v41, v44, v43
	v_div_fmas_f32 v41, v41, v42, v44
	v_div_fixup_f32 v35, v41, v36, v35
	v_mul_f32_e32 v35, v37, v35
	v_cvt_pk_bf16_f32 v41, v34, v35
	v_add_u32_e32 v34, 0xa0, v160
	v_ashrrev_i32_e32 v35, 31, v34
	global_store_dwordx4 v[50:51], v[38:41], off offset:256
	s_nop 1
	v_lshlrev_b64 v[38:39], 12, v[34:35]
	v_mad_i64_i32 v[34:35], s[12:13], v34, s75, v[162:163]
	v_lshl_add_u64 v[34:35], v[34:35], 0, v[144:145]
	v_lshl_add_u64 v[40:41], v[34:35], 0, s[26:27]
	v_add_co_u32_e32 v34, vcc, s5, v34
	s_nop 1
	v_addc_co_u32_e32 v35, vcc, 0, v35, vcc
	global_load_dwordx4 v[34:37], v[34:35], off
	s_waitcnt vmcnt(0)
; __device__ __forceinline__ unsigned cvt_pk_bf16(float lo, float hi) { unsigned r; asm volatile("v_cvt_pk_bf16_f32 %0, %1, %2" : "=v"(r) : "v"(lo), "v"(hi)); return r; }
; __device__ __forceinline__ float bflo(unsigned u) { return __uint_as_float(u << 16); }
; __device__ __forceinline__ float bfhi(unsigned u) { return __uint_as_float(u & 0xffff0000u); }
; __device__ __forceinline__ float silu_f(float v) { return v / (1.f + __expf(-v)); }
;     __device__ __forceinline__ void operator()(const pg8::f32x4 (&acc)[2][2][4][2], const pg8::Unit& u, int wr, int wc, int fr, int fq) const {
;     ...
;             for (int m = 0; m < 4; ++m) { const size_t row = (size_t)(row0 + ai * 128 + m * 16);
; #pragma unroll
;                 for (int bj = 0; bj < 2; ++bj) { const pg8::f32x4 v0 = acc[ai][bj][m][0], v1 = acc[ai][bj][m][1];
;                     const u32x4 gz = *(const u32x4*)(Z + row * DIN + goff + col0 + bj * 128); u32x4 w;
;                     w.x = pg8::cvt_pk_bf16(v0[0] * silu_f(bflo(gz.x)), v0[1] * silu_f(bfhi(gz.x))); w.y = pg8::cvt_pk_bf16(v0[2] * silu_f(bflo(gz.y)), v0[3] * silu_f(bfhi(gz.y)));
;                     w.z = pg8::cvt_pk_bf16(v1[0] * silu_f(bflo(gz.z)), v1[1] * silu_f(bfhi(gz.z))); w.w = pg8::cvt_pk_bf16(v1[2] * silu_f(bflo(gz.w)), v1[3] * silu_f(bfhi(gz.w)));
;                     *(u32x4*)(O + row * DM + coff + col0 + bj * 128) = w; } }
	v_lshlrev_b32_e32 v42, 16, v34
	v_mul_f32_e32 v43, 0xbfb8aa3b, v42
	v_exp_f32_e32 v43, v43
	v_and_b32_e32 v34, 0xffff0000, v34
	v_add_f32_e32 v43, 1.0, v43
	v_div_scale_f32 v44, s[12:13], v43, v43, v42
	v_rcp_f32_e32 v45, v44
	s_nop 0
	v_fma_f32 v46, -v44, v45, 1.0
	v_fmac_f32_e32 v45, v46, v45
	v_div_scale_f32 v46, vcc, v42, v43, v42
	v_mul_f32_e32 v47, v46, v45
	v_fma_f32 v48, -v44, v47, v46
	v_fmac_f32_e32 v47, v48, v45
	v_fma_f32 v44, -v44, v47, v46
	v_div_fmas_f32 v44, v44, v45, v47
	v_div_fixup_f32 v42, v44, v43, v42
	v_mul_f32_e32 v30, v30, v42
	v_mul_f32_e32 v42, 0xbfb8aa3b, v34
	v_exp_f32_e32 v42, v42
	s_nop 0
	v_add_f32_e32 v42, 1.0, v42
	v_div_scale_f32 v43, s[12:13], v42, v42, v34
	v_rcp_f32_e32 v44, v43
	s_nop 0
	v_fma_f32 v45, -v43, v44, 1.0
	v_fmac_f32_e32 v44, v45, v44
	v_div_scale_f32 v45, vcc, v34, v42, v34
	v_mul_f32_e32 v46, v45, v44
	v_fma_f32 v47, -v43, v46, v45
	v_fmac_f32_e32 v46, v47, v44
	v_fma_f32 v43, -v43, v46, v45
	v_div_fmas_f32 v43, v43, v44, v46
	v_div_fixup_f32 v34, v43, v42, v34
	v_mul_f32_e32 v31, v31, v34
	v_cvt_pk_bf16_f32 v30, v30, v31
	v_lshlrev_b32_e32 v31, 16, v35
	v_mul_f32_e32 v34, 0xbfb8aa3b, v31
	v_exp_f32_e32 v34, v34
	s_nop 0
	v_add_f32_e32 v34, 1.0, v34
	v_div_scale_f32 v42, s[12:13], v34, v34, v31
	v_rcp_f32_e32 v43, v42
	s_nop 0
	v_fma_f32 v44, -v42, v43, 1.0
	v_fmac_f32_e32 v43, v44, v43
	v_div_scale_f32 v44, vcc, v31, v34, v31
	v_mul_f32_e32 v45, v44, v43
	v_fma_f32 v46, -v42, v45, v44
	v_fmac_f32_e32 v45, v46, v43
	v_fma_f32 v42, -v42, v45, v44
	v_div_fmas_f32 v42, v42, v43, v45
	v_div_fixup_f32 v31, v42, v34, v31
	v_mul_f32_e32 v31, v32, v31
	v_and_b32_e32 v32, 0xffff0000, v35
	v_mul_f32_e32 v34, 0xbfb8aa3b, v32
	v_exp_f32_e32 v34, v34
	s_nop 0
	v_add_f32_e32 v34, 1.0, v34
	v_div_scale_f32 v35, s[12:13], v34, v34, v32
	v_rcp_f32_e32 v42, v35
	s_nop 0
	v_fma_f32 v43, -v35, v42, 1.0
	v_fmac_f32_e32 v42, v43, v42
	v_div_scale_f32 v43, vcc, v32, v34, v32
	v_mul_f32_e32 v44, v43, v42
	v_fma_f32 v45, -v35, v44, v43
	v_fmac_f32_e32 v44, v45, v42
	v_fma_f32 v35, -v35, v44, v43
	v_div_fmas_f32 v35, v35, v42, v44
	v_div_fixup_f32 v32, v35, v34, v32
	v_mul_f32_e32 v32, v33, v32
	v_cvt_pk_bf16_f32 v31, v31, v32
	v_lshlrev_b32_e32 v32, 16, v36
	v_mul_f32_e32 v33, 0xbfb8aa3b, v32
	v_exp_f32_e32 v33, v33
	s_nop 0
	v_add_f32_e32 v33, 1.0, v33
	v_div_scale_f32 v34, s[12:13], v33, v33, v32
	v_rcp_f32_e32 v35, v34
	s_nop 0
	v_fma_f32 v42, -v34, v35, 1.0
	v_fmac_f32_e32 v35, v42, v35
	v_div_scale_f32 v42, vcc, v32, v33, v32
	v_mul_f32_e32 v43, v42, v35
	v_fma_f32 v44, -v34, v43, v42
	v_fmac_f32_e32 v43, v44, v35
	v_fma_f32 v34, -v34, v43, v42
	v_div_fmas_f32 v34, v34, v35, v43
	v_div_fixup_f32 v32, v34, v33, v32
	v_mul_f32_e32 v26, v26, v32
	v_and_b32_e32 v32, 0xffff0000, v36
	v_mul_f32_e32 v33, 0xbfb8aa3b, v32
	v_exp_f32_e32 v33, v33
	s_nop 0
	v_add_f32_e32 v33, 1.0, v33
	v_div_scale_f32 v34, s[12:13], v33, v33, v32
	v_rcp_f32_e32 v35, v34
	s_nop 0
	v_fma_f32 v36, -v34, v35, 1.0
	v_fmac_f32_e32 v35, v36, v35
	v_div_scale_f32 v36, vcc, v32, v33, v32
	v_mul_f32_e32 v42, v36, v35
	v_fma_f32 v43, -v34, v42, v36
	v_fmac_f32_e32 v42, v43, v35
	v_fma_f32 v34, -v34, v42, v36
	v_div_fmas_f32 v34, v34, v35, v42
	v_div_fixup_f32 v32, v34, v33, v32
	v_mul_f32_e32 v27, v27, v32
	v_cvt_pk_bf16_f32 v32, v26, v27
	v_lshlrev_b32_e32 v26, 16, v37
	v_mul_f32_e32 v27, 0xbfb8aa3b, v26
	v_exp_f32_e32 v27, v27
	s_nop 0
	v_add_f32_e32 v27, 1.0, v27
	v_div_scale_f32 v33, s[12:13], v27, v27, v26
	v_rcp_f32_e32 v34, v33
	s_nop 0
	v_fma_f32 v35, -v33, v34, 1.0
	v_fmac_f32_e32 v34, v35, v34
	v_div_scale_f32 v35, vcc, v26, v27, v26
	v_mul_f32_e32 v36, v35, v34
	v_fma_f32 v42, -v33, v36, v35
	v_fmac_f32_e32 v36, v42, v34
	v_fma_f32 v33, -v33, v36, v35
	v_div_fmas_f32 v33, v33, v34, v36
	v_div_fixup_f32 v26, v33, v27, v26
	v_and_b32_e32 v27, 0xffff0000, v37
	v_mul_f32_e32 v26, v28, v26
	v_mul_f32_e32 v28, 0xbfb8aa3b, v27
	v_exp_f32_e32 v28, v28
	s_nop 0
	v_add_f32_e32 v28, 1.0, v28
	v_div_scale_f32 v33, s[12:13], v28, v28, v27
	v_rcp_f32_e32 v34, v33
	s_nop 0
	v_fma_f32 v35, -v33, v34, 1.0
	v_fmac_f32_e32 v34, v35, v34
	v_div_scale_f32 v35, vcc, v27, v28, v27
	v_mul_f32_e32 v36, v35, v34
	v_fma_f32 v37, -v33, v36, v35
	v_fmac_f32_e32 v36, v37, v34
	v_fma_f32 v33, -v33, v36, v35
	v_div_fmas_f32 v33, v33, v34, v36
	v_div_fixup_f32 v27, v33, v28, v27
	v_mul_f32_e32 v27, v29, v27
	v_cvt_pk_bf16_f32 v33, v26, v27
	v_lshl_add_u64 v[26:27], s[72:73], 0, v[38:39]
	v_lshl_add_u64 v[34:35], v[26:27], 0, v[144:145]
	global_store_dwordx4 v[34:35], v[30:33], off
	global_load_dwordx4 v[26:29], v[40:41], off offset:256
	s_waitcnt vmcnt(0)
; __device__ __forceinline__ unsigned cvt_pk_bf16(float lo, float hi) { unsigned r; asm volatile("v_cvt_pk_bf16_f32 %0, %1, %2" : "=v"(r) : "v"(lo), "v"(hi)); return r; }
; __device__ __forceinline__ float bflo(unsigned u) { return __uint_as_float(u << 16); }
; __device__ __forceinline__ float bfhi(unsigned u) { return __uint_as_float(u & 0xffff0000u); }
; __device__ __forceinline__ float silu_f(float v) { return v / (1.f + __expf(-v)); }
;     __device__ __forceinline__ void operator()(const pg8::f32x4 (&acc)[2][2][4][2], const pg8::Unit& u, int wr, int wc, int fr, int fq) const {
;     ...
;             for (int m = 0; m < 4; ++m) { const size_t row = (size_t)(row0 + ai * 128 + m * 16);
; #pragma unroll
;                 for (int bj = 0; bj < 2; ++bj) { const pg8::f32x4 v0 = acc[ai][bj][m][0], v1 = acc[ai][bj][m][1];
;                     const u32x4 gz = *(const u32x4*)(Z + row * DIN + goff + col0 + bj * 128); u32x4 w;
;                     w.x = pg8::cvt_pk_bf16(v0[0] * silu_f(bflo(gz.x)), v0[1] * silu_f(bfhi(gz.x))); w.y = pg8::cvt_pk_bf16(v0[2] * silu_f(bflo(gz.y)), v0[3] * silu_f(bfhi(gz.y)));
;                     w.z = pg8::cvt_pk_bf16(v1[0] * silu_f(bflo(gz.z)), v1[1] * silu_f(bfhi(gz.z))); w.w = pg8::cvt_pk_bf16(v1[2] * silu_f(bflo(gz.w)), v1[3] * silu_f(bfhi(gz.w)));
;                     *(u32x4*)(O + row * DM + coff + col0 + bj * 128) = w; } }
	v_lshlrev_b32_e32 v30, 16, v26
	v_mul_f32_e32 v31, 0xbfb8aa3b, v30
	v_exp_f32_e32 v31, v31
	v_and_b32_e32 v26, 0xffff0000, v26
	v_add_f32_e32 v31, 1.0, v31
	v_div_scale_f32 v32, s[12:13], v31, v31, v30
	v_rcp_f32_e32 v33, v32
	s_nop 0
	v_fma_f32 v36, -v32, v33, 1.0
	v_fmac_f32_e32 v33, v36, v33
	v_div_scale_f32 v36, vcc, v30, v31, v30
	v_mul_f32_e32 v37, v36, v33
	v_fma_f32 v38, -v32, v37, v36
	v_fmac_f32_e32 v37, v38, v33
	v_fma_f32 v32, -v32, v37, v36
	v_div_fmas_f32 v32, v32, v33, v37
	v_div_fixup_f32 v30, v32, v31, v30
	v_mul_f32_e32 v22, v22, v30
	v_mul_f32_e32 v30, 0xbfb8aa3b, v26
	v_exp_f32_e32 v30, v30
	s_nop 0
	v_add_f32_e32 v30, 1.0, v30
	v_div_scale_f32 v31, s[12:13], v30, v30, v26
	v_rcp_f32_e32 v32, v31
	s_nop 0
	v_fma_f32 v33, -v31, v32, 1.0
	v_fmac_f32_e32 v32, v33, v32
	v_div_scale_f32 v33, vcc, v26, v30, v26
	v_mul_f32_e32 v36, v33, v32
	v_fma_f32 v37, -v31, v36, v33
	v_fmac_f32_e32 v36, v37, v32
	v_fma_f32 v31, -v31, v36, v33
	v_div_fmas_f32 v31, v31, v32, v36
	v_div_fixup_f32 v26, v31, v30, v26
	v_mul_f32_e32 v23, v23, v26
	v_cvt_pk_bf16_f32 v22, v22, v23
	v_lshlrev_b32_e32 v23, 16, v27
	v_mul_f32_e32 v26, 0xbfb8aa3b, v23
	v_exp_f32_e32 v26, v26
	s_nop 0
	v_add_f32_e32 v26, 1.0, v26
	v_div_scale_f32 v30, s[12:13], v26, v26, v23
	v_rcp_f32_e32 v31, v30
	s_nop 0
	v_fma_f32 v32, -v30, v31, 1.0
	v_fmac_f32_e32 v31, v32, v31
	v_div_scale_f32 v32, vcc, v23, v26, v23
	v_mul_f32_e32 v33, v32, v31
	v_fma_f32 v36, -v30, v33, v32
	v_fmac_f32_e32 v33, v36, v31
	v_fma_f32 v30, -v30, v33, v32
	v_div_fmas_f32 v30, v30, v31, v33
	v_div_fixup_f32 v23, v30, v26, v23
	v_mul_f32_e32 v23, v24, v23
	v_and_b32_e32 v24, 0xffff0000, v27
	v_mul_f32_e32 v26, 0xbfb8aa3b, v24
	v_exp_f32_e32 v26, v26
	s_nop 0
	v_add_f32_e32 v26, 1.0, v26
	v_div_scale_f32 v27, s[12:13], v26, v26, v24
	v_rcp_f32_e32 v30, v27
	s_nop 0
	v_fma_f32 v31, -v27, v30, 1.0
	v_fmac_f32_e32 v30, v31, v30
	v_div_scale_f32 v31, vcc, v24, v26, v24
	v_mul_f32_e32 v32, v31, v30
	v_fma_f32 v33, -v27, v32, v31
	v_fmac_f32_e32 v32, v33, v30
	v_fma_f32 v27, -v27, v32, v31
	v_div_fmas_f32 v27, v27, v30, v32
	v_div_fixup_f32 v24, v27, v26, v24
	v_mul_f32_e32 v24, v25, v24
	v_cvt_pk_bf16_f32 v23, v23, v24
	v_lshlrev_b32_e32 v24, 16, v28
	v_mul_f32_e32 v25, 0xbfb8aa3b, v24
	v_exp_f32_e32 v25, v25
	s_nop 0
	v_add_f32_e32 v25, 1.0, v25
	v_div_scale_f32 v26, s[12:13], v25, v25, v24
	v_rcp_f32_e32 v27, v26
	s_nop 0
	v_fma_f32 v30, -v26, v27, 1.0
	v_fmac_f32_e32 v27, v30, v27
	v_div_scale_f32 v30, vcc, v24, v25, v24
	v_mul_f32_e32 v31, v30, v27
	v_fma_f32 v32, -v26, v31, v30
	v_fmac_f32_e32 v31, v32, v27
	v_fma_f32 v26, -v26, v31, v30
	v_div_fmas_f32 v26, v26, v27, v31
	v_div_fixup_f32 v24, v26, v25, v24
	v_mul_f32_e32 v18, v18, v24
	v_and_b32_e32 v24, 0xffff0000, v28
	v_mul_f32_e32 v25, 0xbfb8aa3b, v24
	v_exp_f32_e32 v25, v25
	s_nop 0
	v_add_f32_e32 v25, 1.0, v25
	v_div_scale_f32 v26, s[12:13], v25, v25, v24
	v_rcp_f32_e32 v27, v26
	s_nop 0
	v_fma_f32 v28, -v26, v27, 1.0
	v_fmac_f32_e32 v27, v28, v27
	v_div_scale_f32 v28, vcc, v24, v25, v24
	v_mul_f32_e32 v30, v28, v27
	v_fma_f32 v31, -v26, v30, v28
	v_fmac_f32_e32 v30, v31, v27
	v_fma_f32 v26, -v26, v30, v28
	v_div_fmas_f32 v26, v26, v27, v30
	v_div_fixup_f32 v24, v26, v25, v24
	v_mul_f32_e32 v19, v19, v24
	v_cvt_pk_bf16_f32 v24, v18, v19
	v_lshlrev_b32_e32 v18, 16, v29
	v_mul_f32_e32 v19, 0xbfb8aa3b, v18
	v_exp_f32_e32 v19, v19
	s_nop 0
	v_add_f32_e32 v19, 1.0, v19
	v_div_scale_f32 v25, s[12:13], v19, v19, v18
	v_rcp_f32_e32 v26, v25
	s_nop 0
	v_fma_f32 v27, -v25, v26, 1.0
	v_fmac_f32_e32 v26, v27, v26
	v_div_scale_f32 v27, vcc, v18, v19, v18
	v_mul_f32_e32 v28, v27, v26
	v_fma_f32 v30, -v25, v28, v27
	v_fmac_f32_e32 v28, v30, v26
	v_fma_f32 v25, -v25, v28, v27
	v_div_fmas_f32 v25, v25, v26, v28
	v_div_fixup_f32 v18, v25, v19, v18
	v_and_b32_e32 v19, 0xffff0000, v29
	v_mul_f32_e32 v18, v20, v18
	v_mul_f32_e32 v20, 0xbfb8aa3b, v19
	v_exp_f32_e32 v20, v20
	s_nop 0
	v_add_f32_e32 v20, 1.0, v20
	v_div_scale_f32 v25, s[12:13], v20, v20, v19
	v_rcp_f32_e32 v26, v25
	s_nop 0
	v_fma_f32 v27, -v25, v26, 1.0
	v_fmac_f32_e32 v26, v27, v26
	v_div_scale_f32 v27, vcc, v19, v20, v19
	v_mul_f32_e32 v28, v27, v26
	v_fma_f32 v29, -v25, v28, v27
	v_fmac_f32_e32 v28, v29, v26
	v_fma_f32 v25, -v25, v28, v27
	v_div_fmas_f32 v25, v25, v26, v28
	v_div_fixup_f32 v19, v25, v20, v19
	v_mul_f32_e32 v19, v21, v19
	v_cvt_pk_bf16_f32 v25, v18, v19
	v_add_u32_e32 v18, 0xb0, v160
	v_ashrrev_i32_e32 v19, 31, v18
	global_store_dwordx4 v[34:35], v[22:25], off offset:256
	s_nop 1
	v_lshlrev_b64 v[22:23], 12, v[18:19]
	v_mad_i64_i32 v[18:19], s[12:13], v18, s75, v[162:163]
	v_lshl_add_u64 v[18:19], v[18:19], 0, v[144:145]
	v_lshl_add_u64 v[24:25], v[18:19], 0, s[26:27]
	v_add_co_u32_e32 v18, vcc, s5, v18
	s_nop 1
	v_addc_co_u32_e32 v19, vcc, 0, v19, vcc
	global_load_dwordx4 v[18:21], v[18:19], off
	s_waitcnt vmcnt(0)
; __device__ __forceinline__ unsigned cvt_pk_bf16(float lo, float hi) { unsigned r; asm volatile("v_cvt_pk_bf16_f32 %0, %1, %2" : "=v"(r) : "v"(lo), "v"(hi)); return r; }
; __device__ __forceinline__ float bflo(unsigned u) { return __uint_as_float(u << 16); }
; __device__ __forceinline__ float bfhi(unsigned u) { return __uint_as_float(u & 0xffff0000u); }
; __device__ __forceinline__ float silu_f(float v) { return v / (1.f + __expf(-v)); }
;     __device__ __forceinline__ void operator()(const pg8::f32x4 (&acc)[2][2][4][2], const pg8::Unit& u, int wr, int wc, int fr, int fq) const {
;     ...
;             for (int m = 0; m < 4; ++m) { const size_t row = (size_t)(row0 + ai * 128 + m * 16);
; #pragma unroll
;                 for (int bj = 0; bj < 2; ++bj) { const pg8::f32x4 v0 = acc[ai][bj][m][0], v1 = acc[ai][bj][m][1];
;                     const u32x4 gz = *(const u32x4*)(Z + row * DIN + goff + col0 + bj * 128); u32x4 w;
;                     w.x = pg8::cvt_pk_bf16(v0[0] * silu_f(bflo(gz.x)), v0[1] * silu_f(bfhi(gz.x))); w.y = pg8::cvt_pk_bf16(v0[2] * silu_f(bflo(gz.y)), v0[3] * silu_f(bfhi(gz.y)));
;                     w.z = pg8::cvt_pk_bf16(v1[0] * silu_f(bflo(gz.z)), v1[1] * silu_f(bfhi(gz.z))); w.w = pg8::cvt_pk_bf16(v1[2] * silu_f(bflo(gz.w)), v1[3] * silu_f(bfhi(gz.w)));
;                     *(u32x4*)(O + row * DM + coff + col0 + bj * 128) = w; } }
	v_lshlrev_b32_e32 v26, 16, v18
	v_mul_f32_e32 v27, 0xbfb8aa3b, v26
	v_exp_f32_e32 v27, v27
	v_and_b32_e32 v18, 0xffff0000, v18
	v_add_f32_e32 v27, 1.0, v27
	v_div_scale_f32 v28, s[12:13], v27, v27, v26
	v_rcp_f32_e32 v29, v28
	s_nop 0
	v_fma_f32 v30, -v28, v29, 1.0
	v_fmac_f32_e32 v29, v30, v29
	v_div_scale_f32 v30, vcc, v26, v27, v26
	v_mul_f32_e32 v31, v30, v29
	v_fma_f32 v32, -v28, v31, v30
	v_fmac_f32_e32 v31, v32, v29
	v_fma_f32 v28, -v28, v31, v30
	v_div_fmas_f32 v28, v28, v29, v31
	v_div_fixup_f32 v26, v28, v27, v26
	v_mul_f32_e32 v14, v14, v26
	v_mul_f32_e32 v26, 0xbfb8aa3b, v18
	v_exp_f32_e32 v26, v26
	s_nop 0
	v_add_f32_e32 v26, 1.0, v26
	v_div_scale_f32 v27, s[12:13], v26, v26, v18
	v_rcp_f32_e32 v28, v27
	s_nop 0
	v_fma_f32 v29, -v27, v28, 1.0
	v_fmac_f32_e32 v28, v29, v28
	v_div_scale_f32 v29, vcc, v18, v26, v18
	v_mul_f32_e32 v30, v29, v28
	v_fma_f32 v31, -v27, v30, v29
	v_fmac_f32_e32 v30, v31, v28
	v_fma_f32 v27, -v27, v30, v29
	v_div_fmas_f32 v27, v27, v28, v30
	v_div_fixup_f32 v18, v27, v26, v18
	v_mul_f32_e32 v15, v15, v18
	v_cvt_pk_bf16_f32 v14, v14, v15
	v_lshlrev_b32_e32 v15, 16, v19
	v_mul_f32_e32 v18, 0xbfb8aa3b, v15
	v_exp_f32_e32 v18, v18
	s_nop 0
	v_add_f32_e32 v18, 1.0, v18
	v_div_scale_f32 v26, s[12:13], v18, v18, v15
	v_rcp_f32_e32 v27, v26
	s_nop 0
	v_fma_f32 v28, -v26, v27, 1.0
	v_fmac_f32_e32 v27, v28, v27
	v_div_scale_f32 v28, vcc, v15, v18, v15
	v_mul_f32_e32 v29, v28, v27
	v_fma_f32 v30, -v26, v29, v28
	v_fmac_f32_e32 v29, v30, v27
	v_fma_f32 v26, -v26, v29, v28
	v_div_fmas_f32 v26, v26, v27, v29
	v_div_fixup_f32 v15, v26, v18, v15
	v_mul_f32_e32 v15, v16, v15
	v_and_b32_e32 v16, 0xffff0000, v19
	v_mul_f32_e32 v18, 0xbfb8aa3b, v16
	v_exp_f32_e32 v18, v18
	s_nop 0
	v_add_f32_e32 v18, 1.0, v18
	v_div_scale_f32 v19, s[12:13], v18, v18, v16
	v_rcp_f32_e32 v26, v19
	s_nop 0
	v_fma_f32 v27, -v19, v26, 1.0
	v_fmac_f32_e32 v26, v27, v26
	v_div_scale_f32 v27, vcc, v16, v18, v16
	v_mul_f32_e32 v28, v27, v26
	v_fma_f32 v29, -v19, v28, v27
	v_fmac_f32_e32 v28, v29, v26
	v_fma_f32 v19, -v19, v28, v27
	v_div_fmas_f32 v19, v19, v26, v28
	v_div_fixup_f32 v16, v19, v18, v16
	v_mul_f32_e32 v16, v17, v16
	v_cvt_pk_bf16_f32 v15, v15, v16
	v_lshlrev_b32_e32 v16, 16, v20
	v_mul_f32_e32 v17, 0xbfb8aa3b, v16
	v_exp_f32_e32 v17, v17
	s_nop 0
	v_add_f32_e32 v17, 1.0, v17
	v_div_scale_f32 v18, s[12:13], v17, v17, v16
	v_rcp_f32_e32 v19, v18
	s_nop 0
	v_fma_f32 v26, -v18, v19, 1.0
	v_fmac_f32_e32 v19, v26, v19
	v_div_scale_f32 v26, vcc, v16, v17, v16
	v_mul_f32_e32 v27, v26, v19
	v_fma_f32 v28, -v18, v27, v26
	v_fmac_f32_e32 v27, v28, v19
	v_fma_f32 v18, -v18, v27, v26
	v_div_fmas_f32 v18, v18, v19, v27
	v_div_fixup_f32 v16, v18, v17, v16
	v_mul_f32_e32 v10, v10, v16
	v_and_b32_e32 v16, 0xffff0000, v20
	v_mul_f32_e32 v17, 0xbfb8aa3b, v16
	v_exp_f32_e32 v17, v17
	s_nop 0
	v_add_f32_e32 v17, 1.0, v17
	v_div_scale_f32 v18, s[12:13], v17, v17, v16
	v_rcp_f32_e32 v19, v18
	s_nop 0
	v_fma_f32 v20, -v18, v19, 1.0
	v_fmac_f32_e32 v19, v20, v19
	v_div_scale_f32 v20, vcc, v16, v17, v16
	v_mul_f32_e32 v26, v20, v19
	v_fma_f32 v27, -v18, v26, v20
	v_fmac_f32_e32 v26, v27, v19
	v_fma_f32 v18, -v18, v26, v20
	v_div_fmas_f32 v18, v18, v19, v26
	v_div_fixup_f32 v16, v18, v17, v16
	v_mul_f32_e32 v11, v11, v16
	v_cvt_pk_bf16_f32 v16, v10, v11
	v_lshlrev_b32_e32 v10, 16, v21
	v_mul_f32_e32 v11, 0xbfb8aa3b, v10
	v_exp_f32_e32 v11, v11
	s_nop 0
	v_add_f32_e32 v11, 1.0, v11
	v_div_scale_f32 v17, s[12:13], v11, v11, v10
	v_rcp_f32_e32 v18, v17
	s_nop 0
	v_fma_f32 v19, -v17, v18, 1.0
	v_fmac_f32_e32 v18, v19, v18
	v_div_scale_f32 v19, vcc, v10, v11, v10
	v_mul_f32_e32 v20, v19, v18
	v_fma_f32 v26, -v17, v20, v19
	v_fmac_f32_e32 v20, v26, v18
	v_fma_f32 v17, -v17, v20, v19
	v_div_fmas_f32 v17, v17, v18, v20
	v_div_fixup_f32 v10, v17, v11, v10
	v_and_b32_e32 v11, 0xffff0000, v21
	v_mul_f32_e32 v10, v12, v10
	v_mul_f32_e32 v12, 0xbfb8aa3b, v11
	v_exp_f32_e32 v12, v12
	s_nop 0
	v_add_f32_e32 v12, 1.0, v12
	v_div_scale_f32 v17, s[12:13], v12, v12, v11
	v_rcp_f32_e32 v18, v17
	s_nop 0
	v_fma_f32 v19, -v17, v18, 1.0
	v_fmac_f32_e32 v18, v19, v18
	v_div_scale_f32 v19, vcc, v11, v12, v11
	v_mul_f32_e32 v20, v19, v18
	v_fma_f32 v21, -v17, v20, v19
	v_fmac_f32_e32 v20, v21, v18
	v_fma_f32 v17, -v17, v20, v19
	v_div_fmas_f32 v17, v17, v18, v20
	v_div_fixup_f32 v11, v17, v12, v11
	v_mul_f32_e32 v11, v13, v11
	v_cvt_pk_bf16_f32 v17, v10, v11
	v_lshl_add_u64 v[10:11], s[72:73], 0, v[22:23]
	v_lshl_add_u64 v[18:19], v[10:11], 0, v[144:145]
	global_store_dwordx4 v[18:19], v[14:17], off
	global_load_dwordx4 v[10:13], v[24:25], off offset:256
	s_waitcnt vmcnt(0)
; __device__ __forceinline__ unsigned cvt_pk_bf16(float lo, float hi) { unsigned r; asm volatile("v_cvt_pk_bf16_f32 %0, %1, %2" : "=v"(r) : "v"(lo), "v"(hi)); return r; }
; #define PG8_BAR __builtin_amdgcn_s_barrier()
; __device__ __forceinline__ float bflo(unsigned u) { return __uint_as_float(u << 16); }
; __device__ __forceinline__ float bfhi(unsigned u) { return __uint_as_float(u & 0xffff0000u); }
; __device__ __forceinline__ float silu_f(float v) { return v / (1.f + __expf(-v)); }
; template <class Epi, class Sched, bool ALIGN_EPI>
; __device__ __forceinline__ void gemm_phase(PG8_LAS unsigned char* lds, const Gemm g, const Sched& S, const Epi& E) {
;     ...
;         if constexpr (ALIGN_EPI) { if (wr == 0) PG8_BAR; }
;         E(acc, cur, wr, wc, fr, fq);
;         if (!has_next) break;
; #pragma unroll
;         for (int a = 0; a < 2; ++a)
; #pragma unroll
;             for (int b = 0; b < 2; ++b)
; #pragma unroll
;                 for (int m = 0; m < 4; ++m)
; #pragma unroll
;                     for (int n = 0; n < 2; ++n) acc[a][b][m][n] = (f32x4){0.f, 0.f, 0.f, 0.f};
;         cur = nxt; cA = nA; cB = nB; ++ui;
;         if constexpr (ALIGN_EPI) { if (wr == 1) PG8_BAR; }
;     }
;     __device__ __forceinline__ void operator()(const pg8::f32x4 (&acc)[2][2][4][2], const pg8::Unit& u, int wr, int wc, int fr, int fq) const {
;     ...
;             for (int m = 0; m < 4; ++m) { const size_t row = (size_t)(row0 + ai * 128 + m * 16);
; #pragma unroll
;                 for (int bj = 0; bj < 2; ++bj) { const pg8::f32x4 v0 = acc[ai][bj][m][0], v1 = acc[ai][bj][m][1];
;                     const u32x4 gz = *(const u32x4*)(Z + row * DIN + goff + col0 + bj * 128); u32x4 w;
;                     w.x = pg8::cvt_pk_bf16(v0[0] * silu_f(bflo(gz.x)), v0[1] * silu_f(bfhi(gz.x))); w.y = pg8::cvt_pk_bf16(v0[2] * silu_f(bflo(gz.y)), v0[3] * silu_f(bfhi(gz.y)));
;                     w.z = pg8::cvt_pk_bf16(v1[0] * silu_f(bflo(gz.z)), v1[1] * silu_f(bfhi(gz.z))); w.w = pg8::cvt_pk_bf16(v1[2] * silu_f(bflo(gz.w)), v1[3] * silu_f(bfhi(gz.w)));
;                     *(u32x4*)(O + row * DM + coff + col0 + bj * 128) = w; } }
	v_lshlrev_b32_e32 v14, 16, v10
	v_mul_f32_e32 v15, 0xbfb8aa3b, v14
	v_exp_f32_e32 v15, v15
	v_and_b32_e32 v10, 0xffff0000, v10
	v_add_f32_e32 v15, 1.0, v15
	v_div_scale_f32 v16, s[12:13], v15, v15, v14
	v_rcp_f32_e32 v17, v16
	s_nop 0
	v_fma_f32 v20, -v16, v17, 1.0
	v_fmac_f32_e32 v17, v20, v17
	v_div_scale_f32 v20, vcc, v14, v15, v14
	v_mul_f32_e32 v21, v20, v17
	v_fma_f32 v22, -v16, v21, v20
	v_fmac_f32_e32 v21, v22, v17
	v_fma_f32 v16, -v16, v21, v20
	v_div_fmas_f32 v16, v16, v17, v21
	v_div_fixup_f32 v14, v16, v15, v14
	v_mul_f32_e32 v6, v6, v14
	v_mul_f32_e32 v14, 0xbfb8aa3b, v10
	v_exp_f32_e32 v14, v14
	s_nop 0
	v_add_f32_e32 v14, 1.0, v14
	v_div_scale_f32 v15, s[12:13], v14, v14, v10
	v_rcp_f32_e32 v16, v15
	s_nop 0
	v_fma_f32 v17, -v15, v16, 1.0
	v_fmac_f32_e32 v16, v17, v16
	v_div_scale_f32 v17, vcc, v10, v14, v10
	v_mul_f32_e32 v20, v17, v16
	v_fma_f32 v21, -v15, v20, v17
	v_fmac_f32_e32 v20, v21, v16
	v_fma_f32 v15, -v15, v20, v17
	v_div_fmas_f32 v15, v15, v16, v20
	v_div_fixup_f32 v10, v15, v14, v10
	v_mul_f32_e32 v7, v7, v10
	v_cvt_pk_bf16_f32 v6, v6, v7
	v_lshlrev_b32_e32 v7, 16, v11
	v_mul_f32_e32 v10, 0xbfb8aa3b, v7
	v_exp_f32_e32 v10, v10
	s_nop 0
	v_add_f32_e32 v10, 1.0, v10
	v_div_scale_f32 v14, s[12:13], v10, v10, v7
	v_rcp_f32_e32 v15, v14
	s_nop 0
	v_fma_f32 v16, -v14, v15, 1.0
	v_fmac_f32_e32 v15, v16, v15
	v_div_scale_f32 v16, vcc, v7, v10, v7
	v_mul_f32_e32 v17, v16, v15
	v_fma_f32 v20, -v14, v17, v16
	v_fmac_f32_e32 v17, v20, v15
	v_fma_f32 v14, -v14, v17, v16
	v_div_fmas_f32 v14, v14, v15, v17
	v_div_fixup_f32 v7, v14, v10, v7
	v_mul_f32_e32 v7, v8, v7
	v_and_b32_e32 v8, 0xffff0000, v11
	v_mul_f32_e32 v10, 0xbfb8aa3b, v8
	v_exp_f32_e32 v10, v10
	s_nop 0
	v_add_f32_e32 v10, 1.0, v10
	v_div_scale_f32 v11, s[12:13], v10, v10, v8
	v_rcp_f32_e32 v14, v11
	s_nop 0
	v_fma_f32 v15, -v11, v14, 1.0
	v_fmac_f32_e32 v14, v15, v14
	v_div_scale_f32 v15, vcc, v8, v10, v8
	v_mul_f32_e32 v16, v15, v14
	v_fma_f32 v17, -v11, v16, v15
	v_fmac_f32_e32 v16, v17, v14
	v_fma_f32 v11, -v11, v16, v15
	v_div_fmas_f32 v11, v11, v14, v16
	v_div_fixup_f32 v8, v11, v10, v8
	v_mul_f32_e32 v8, v9, v8
	v_cvt_pk_bf16_f32 v7, v7, v8
	v_lshlrev_b32_e32 v8, 16, v12
	v_mul_f32_e32 v9, 0xbfb8aa3b, v8
	v_exp_f32_e32 v9, v9
	s_nop 0
	v_add_f32_e32 v9, 1.0, v9
	v_div_scale_f32 v10, s[12:13], v9, v9, v8
	v_rcp_f32_e32 v11, v10
	s_nop 0
	v_fma_f32 v14, -v10, v11, 1.0
	v_fmac_f32_e32 v11, v14, v11
	v_div_scale_f32 v14, vcc, v8, v9, v8
	v_mul_f32_e32 v15, v14, v11
	v_fma_f32 v16, -v10, v15, v14
	v_fmac_f32_e32 v15, v16, v11
	v_fma_f32 v10, -v10, v15, v14
	v_div_fmas_f32 v10, v10, v11, v15
	v_div_fixup_f32 v8, v10, v9, v8
	v_mul_f32_e32 v2, v2, v8
	v_and_b32_e32 v8, 0xffff0000, v12
	v_mul_f32_e32 v9, 0xbfb8aa3b, v8
	v_exp_f32_e32 v9, v9
	s_nop 0
	v_add_f32_e32 v9, 1.0, v9
	v_div_scale_f32 v10, s[12:13], v9, v9, v8
	v_rcp_f32_e32 v11, v10
	s_nop 0
	v_fma_f32 v12, -v10, v11, 1.0
	v_fmac_f32_e32 v11, v12, v11
	v_div_scale_f32 v12, vcc, v8, v9, v8
	v_mul_f32_e32 v14, v12, v11
	v_fma_f32 v15, -v10, v14, v12
	v_fmac_f32_e32 v14, v15, v11
	v_fma_f32 v10, -v10, v14, v12
	v_div_fmas_f32 v10, v10, v11, v14
	v_div_fixup_f32 v8, v10, v9, v8
	v_mul_f32_e32 v3, v3, v8
	v_cvt_pk_bf16_f32 v8, v2, v3
	v_lshlrev_b32_e32 v2, 16, v13
	v_mul_f32_e32 v3, 0xbfb8aa3b, v2
	v_exp_f32_e32 v3, v3
	s_nop 0
	v_add_f32_e32 v3, 1.0, v3
	v_div_scale_f32 v9, s[12:13], v3, v3, v2
	v_rcp_f32_e32 v10, v9
	s_nop 0
	v_fma_f32 v11, -v9, v10, 1.0
	v_fmac_f32_e32 v10, v11, v10
	v_div_scale_f32 v11, vcc, v2, v3, v2
	v_mul_f32_e32 v12, v11, v10
	v_fma_f32 v14, -v9, v12, v11
	v_fmac_f32_e32 v12, v14, v10
	v_fma_f32 v9, -v9, v12, v11
	v_div_fmas_f32 v9, v9, v10, v12
	v_div_fixup_f32 v2, v9, v3, v2
	v_and_b32_e32 v3, 0xffff0000, v13
	v_mul_f32_e32 v2, v4, v2
	v_mul_f32_e32 v4, 0xbfb8aa3b, v3
	v_exp_f32_e32 v4, v4
	s_nop 0
	v_add_f32_e32 v4, 1.0, v4
	v_div_scale_f32 v9, s[12:13], v4, v4, v3
	v_rcp_f32_e32 v10, v9
	s_nop 0
	v_fma_f32 v11, -v9, v10, 1.0
	v_fmac_f32_e32 v10, v11, v10
	v_div_scale_f32 v11, vcc, v3, v4, v3
	v_mul_f32_e32 v12, v11, v10
	v_fma_f32 v13, -v9, v12, v11
	v_fmac_f32_e32 v12, v13, v10
	v_fma_f32 v9, -v9, v12, v11
	v_div_fmas_f32 v9, v9, v10, v12
	v_div_fixup_f32 v3, v9, v4, v3
	s_andn2_b64 vcc, exec, s[40:41]
	v_mul_f32_e32 v3, v5, v3
	v_cvt_pk_bf16_f32 v9, v2, v3
	global_store_dwordx4 v[18:19], v[6:9], off offset:256
	s_cbranch_vccnz .LBB0_544
	s_andn2_b64 vcc, exec, s[36:37]
	s_cbranch_vccnz .LBB0_543
	s_barrier
	s_branch .LBB0_543
